# prologue: silu table loads batched, adaLN GEMV k-loop software-pipelined (next 8 rows in flight)
# speedup vs baseline: 1.0046x; 1.0046x over previous
; __device__ __forceinline__ void prologue_phase(const Args& a, LAS unsigned char* lds) {
;     ...
;         for (int i = tid; i < 5 * DM; i += 512) { const float cv = i < 4 * DM ? a.c[i] : a.c_ctx[i - 4 * DM]; sil[i] = cv / (1.0f + __expf(-cv)); }
;         __syncthreads();
;         float acc[5][2];
; #pragma unroll
;         for (int s = 0; s < 5; ++s) { acc[s][0] = 0.f; acc[s][1] = 0.f; }
;         const float* wp = a.ada_w + ((size_t)l * DM + 128 * w) * 6144 + j;
; #pragma unroll 8
;         for (int kk = 0; kk < 128; ++kk) { const int k = 128 * w + kk; const f32x2_t wv = *(const f32x2_t*)(wp + (size_t)kk * 6144);
.LBB0_38:
	global_load_dword v16, v[4:5], off
	v_lshl_add_u64 v[4:5], v[4:5], 0, s[6:7]
	global_load_dword v17, v[4:5], off
	v_lshl_add_u64 v[4:5], v[4:5], 0, s[6:7]
	global_load_dword v18, v[4:5], off
	v_lshl_add_u64 v[4:5], v[4:5], 0, s[6:7]
	global_load_dword v19, v[4:5], off
	v_lshl_add_u64 v[4:5], v[4:5], 0, s[6:7]
	global_load_dword v20, v[4:5], off
	v_lshl_add_u64 v[4:5], v[4:5], 0, s[6:7]
	global_load_dword v21, v[4:5], off
	v_lshl_add_u64 v[4:5], v[4:5], 0, s[6:7]
	global_load_dword v22, v[4:5], off
	v_lshl_add_u64 v[4:5], v[4:5], 0, s[6:7]
	global_load_dword v23, v[4:5], off
	v_lshl_add_u64 v[4:5], v[4:5], 0, s[6:7]
	s_mov_b64 s[10:11], 0x4000
	v_lshl_add_u64 v[0:1], v[0:1], 0, s[10:11]
	global_load_dword v24, v[0:1], off
	global_load_dword v25, v[0:1], off offset:2048
	s_waitcnt vmcnt(0)
	v_mul_f32_e32 v9, 0xbfb8aa3b, v16
	v_exp_f32_e32 v9, v9
	s_nop 0
	v_add_f32_e32 v9, 1.0, v9
	v_div_scale_f32 v10, s[10:11], v9, v9, v16
	v_rcp_f32_e32 v11, v10
	v_div_scale_f32 v12, vcc, v16, v9, v16
	v_fma_f32 v13, -v10, v11, 1.0
	v_fmac_f32_e32 v11, v13, v11
	v_mul_f32_e32 v13, v12, v11
	v_fma_f32 v15, -v10, v13, v12
	v_fmac_f32_e32 v13, v15, v11
	v_fma_f32 v10, -v10, v13, v12
	v_div_fmas_f32 v10, v10, v11, v13
	v_div_fixup_f32 v8, v10, v9, v16
	ds_write_b32 v6, v8
	v_mul_f32_e32 v9, 0xbfb8aa3b, v17
	v_exp_f32_e32 v9, v9
	s_nop 0
	v_add_f32_e32 v9, 1.0, v9
	v_div_scale_f32 v10, s[10:11], v9, v9, v17
	v_rcp_f32_e32 v11, v10
	v_div_scale_f32 v12, vcc, v17, v9, v17
	v_fma_f32 v13, -v10, v11, 1.0
	v_fmac_f32_e32 v11, v13, v11
	v_mul_f32_e32 v13, v12, v11
	v_fma_f32 v15, -v10, v13, v12
	v_fmac_f32_e32 v13, v15, v11
	v_fma_f32 v10, -v10, v13, v12
	v_div_fmas_f32 v10, v10, v11, v13
	v_div_fixup_f32 v8, v10, v9, v17
	ds_write_b32 v6, v8 offset:2048
	v_mul_f32_e32 v9, 0xbfb8aa3b, v18
	v_exp_f32_e32 v9, v9
	s_nop 0
	v_add_f32_e32 v9, 1.0, v9
	v_div_scale_f32 v10, s[10:11], v9, v9, v18
	v_rcp_f32_e32 v11, v10
	v_div_scale_f32 v12, vcc, v18, v9, v18
	v_fma_f32 v13, -v10, v11, 1.0
	v_fmac_f32_e32 v11, v13, v11
	v_mul_f32_e32 v13, v12, v11
	v_fma_f32 v15, -v10, v13, v12
	v_fmac_f32_e32 v13, v15, v11
	v_fma_f32 v10, -v10, v13, v12
	v_div_fmas_f32 v10, v10, v11, v13
	v_div_fixup_f32 v8, v10, v9, v18
	ds_write_b32 v6, v8 offset:4096
	v_mul_f32_e32 v9, 0xbfb8aa3b, v19
	v_exp_f32_e32 v9, v9
	s_nop 0
	v_add_f32_e32 v9, 1.0, v9
	v_div_scale_f32 v10, s[10:11], v9, v9, v19
	v_rcp_f32_e32 v11, v10
	v_div_scale_f32 v12, vcc, v19, v9, v19
	v_fma_f32 v13, -v10, v11, 1.0
	v_fmac_f32_e32 v11, v13, v11
	v_mul_f32_e32 v13, v12, v11
	v_fma_f32 v15, -v10, v13, v12
	v_fmac_f32_e32 v13, v15, v11
	v_fma_f32 v10, -v10, v13, v12
	v_div_fmas_f32 v10, v10, v11, v13
	v_div_fixup_f32 v8, v10, v9, v19
	ds_write_b32 v6, v8 offset:6144
	v_mul_f32_e32 v9, 0xbfb8aa3b, v20
	v_exp_f32_e32 v9, v9
	s_nop 0
	v_add_f32_e32 v9, 1.0, v9
	v_div_scale_f32 v10, s[10:11], v9, v9, v20
	v_rcp_f32_e32 v11, v10
	v_div_scale_f32 v12, vcc, v20, v9, v20
	v_fma_f32 v13, -v10, v11, 1.0
	v_fmac_f32_e32 v11, v13, v11
	v_mul_f32_e32 v13, v12, v11
	v_fma_f32 v15, -v10, v13, v12
	v_fmac_f32_e32 v13, v15, v11
	v_fma_f32 v10, -v10, v13, v12
	v_div_fmas_f32 v10, v10, v11, v13
	v_div_fixup_f32 v8, v10, v9, v20
	ds_write_b32 v6, v8 offset:8192
	v_mul_f32_e32 v9, 0xbfb8aa3b, v21
	v_exp_f32_e32 v9, v9
	s_nop 0
	v_add_f32_e32 v9, 1.0, v9
	v_div_scale_f32 v10, s[10:11], v9, v9, v21
	v_rcp_f32_e32 v11, v10
	v_div_scale_f32 v12, vcc, v21, v9, v21
	v_fma_f32 v13, -v10, v11, 1.0
	v_fmac_f32_e32 v11, v13, v11
	v_mul_f32_e32 v13, v12, v11
	v_fma_f32 v15, -v10, v13, v12
	v_fmac_f32_e32 v13, v15, v11
	v_fma_f32 v10, -v10, v13, v12
	v_div_fmas_f32 v10, v10, v11, v13
	v_div_fixup_f32 v8, v10, v9, v21
	ds_write_b32 v6, v8 offset:10240
	v_mul_f32_e32 v9, 0xbfb8aa3b, v22
	v_exp_f32_e32 v9, v9
	s_nop 0
	v_add_f32_e32 v9, 1.0, v9
	v_div_scale_f32 v10, s[10:11], v9, v9, v22
	v_rcp_f32_e32 v11, v10
	v_div_scale_f32 v12, vcc, v22, v9, v22
	v_fma_f32 v13, -v10, v11, 1.0
	v_fmac_f32_e32 v11, v13, v11
	v_mul_f32_e32 v13, v12, v11
	v_fma_f32 v15, -v10, v13, v12
	v_fmac_f32_e32 v13, v15, v11
	v_fma_f32 v10, -v10, v13, v12
	v_div_fmas_f32 v10, v10, v11, v13
	v_div_fixup_f32 v8, v10, v9, v22
	ds_write_b32 v6, v8 offset:12288
	v_mul_f32_e32 v9, 0xbfb8aa3b, v23
	v_exp_f32_e32 v9, v9
	s_nop 0
	v_add_f32_e32 v9, 1.0, v9
	v_div_scale_f32 v10, s[10:11], v9, v9, v23
	v_rcp_f32_e32 v11, v10
	v_div_scale_f32 v12, vcc, v23, v9, v23
	v_fma_f32 v13, -v10, v11, 1.0
	v_fmac_f32_e32 v11, v13, v11
	v_mul_f32_e32 v13, v12, v11
	v_fma_f32 v15, -v10, v13, v12
	v_fmac_f32_e32 v13, v15, v11
	v_fma_f32 v10, -v10, v13, v12
	v_div_fmas_f32 v10, v10, v11, v13
	v_div_fixup_f32 v8, v10, v9, v23
	ds_write_b32 v6, v8 offset:14336
	v_mul_f32_e32 v9, 0xbfb8aa3b, v24
	v_exp_f32_e32 v9, v9
	s_nop 0
	v_add_f32_e32 v9, 1.0, v9
	v_div_scale_f32 v10, s[10:11], v9, v9, v24
	v_rcp_f32_e32 v11, v10
	v_div_scale_f32 v12, vcc, v24, v9, v24
	v_fma_f32 v13, -v10, v11, 1.0
	v_fmac_f32_e32 v11, v13, v11
	v_mul_f32_e32 v13, v12, v11
	v_fma_f32 v15, -v10, v13, v12
	v_fmac_f32_e32 v13, v15, v11
	v_fma_f32 v10, -v10, v13, v12
	v_div_fmas_f32 v10, v10, v11, v13
	v_div_fixup_f32 v8, v10, v9, v24
	ds_write_b32 v6, v8 offset:16384
	v_mul_f32_e32 v9, 0xbfb8aa3b, v25
	v_exp_f32_e32 v9, v9
	s_nop 0
	v_add_f32_e32 v9, 1.0, v9
	v_div_scale_f32 v10, s[10:11], v9, v9, v25
	v_rcp_f32_e32 v11, v10
	v_div_scale_f32 v12, vcc, v25, v9, v25
	v_fma_f32 v13, -v10, v11, 1.0
	v_fmac_f32_e32 v11, v13, v11
	v_mul_f32_e32 v13, v12, v11
	v_fma_f32 v15, -v10, v13, v12
	v_fmac_f32_e32 v13, v15, v11
	v_fma_f32 v10, -v10, v13, v12
	v_div_fmas_f32 v10, v10, v11, v13
	v_div_fixup_f32 v8, v10, v9, v25
	ds_write_b32 v6, v8 offset:18432
	s_or_b64 exec, exec, s[4:5]
	s_lshl_b32 s3, s2, 7
	s_add_i32 s4, s3, 0xffffe800
	s_cmp_lt_u32 s2, 48
	s_cselect_b32 s3, s3, s4
	s_lshl_b32 s10, s14, 7
	s_cmp_gt_u32 s2, 47
	s_cselect_b64 s[4:5], -1, 0
	s_load_dwordx2 s[6:7], s[0:1], 0x20
	s_and_b64 s[8:9], s[4:5], exec
	s_cselect_b32 s8, 0x400, 0
	s_add_i32 s9, s8, s10
	s_mul_hi_u32 s10, s9, 0x6000
	s_mulk_i32 s9, 0x6000
	v_lshlrev_b32_e32 v15, 1, v14
	s_waitcnt lgkmcnt(0)
	s_add_u32 s6, s6, s9
	v_or_b32_e32 v4, s3, v15
	s_addc_u32 s7, s7, s10
	v_mov_b32_e32 v5, 0
	v_lshl_add_u64 v[0:1], v[4:5], 2, s[6:7]
	s_lshl_b32 s6, s14, 9
	s_add_i32 s6, s6, 0
	s_movk_i32 s8, 0x6000
	s_add_i32 s9, s6, 0x8000
	s_mov_b64 s[6:7], 0
	s_mov_b32 s10, 0xc000
	s_mov_b32 s11, 0x12000
	s_mov_b32 s12, 0x18000
	s_mov_b32 s13, 0x1e000
	s_mov_b32 s15, 0x24000
	s_mov_b32 s16, 0x2a000
	v_mov_b32_e32 v4, v5
	v_mov_b32_e32 v6, v5
	v_mov_b32_e32 v7, v5
	v_mov_b32_e32 v8, v5
	v_mov_b32_e32 v9, v5
	v_mov_b32_e32 v10, v5
	v_mov_b32_e32 v11, v5
	v_mov_b32_e32 v12, v5
	v_mov_b32_e32 v13, v5
	s_barrier
; __device__ __forceinline__ void prologue_phase(const Args& a, LAS unsigned char* lds) {
;     ...
;         const float* wp = a.ada_w + ((size_t)l * DM + 128 * w) * 6144 + j;
; #pragma unroll 8
;         for (int kk = 0; kk < 128; ++kk) { const int k = 128 * w + kk; const f32x2_t wv = *(const f32x2_t*)(wp + (size_t)kk * 6144);
; #pragma unroll
;             for (int s = 0; s < 5; ++s) { const float sv = sil[s * DM + k]; acc[s][0] += sv * wv.x; acc[s][1] += sv * wv.y; } }
.LBB0_40:
	s_mov_b64 s[20:21], 0x6000
	v_lshl_add_u64 v[108:109], v[0:1], 0, s[6:7]
	s_add_u32 s6, s6, 0x30000
	s_addc_u32 s7, s7, 0
	global_load_dwordx2 v[56:57], v[108:109], off
	v_lshl_add_u64 v[110:111], v[108:109], 0, s[20:21]
	global_load_dwordx2 v[58:59], v[110:111], off
	v_lshl_add_u64 v[112:113], v[110:111], 0, s[20:21]
	global_load_dwordx2 v[60:61], v[112:113], off
	v_lshl_add_u64 v[114:115], v[112:113], 0, s[20:21]
	global_load_dwordx2 v[62:63], v[114:115], off
	v_lshl_add_u64 v[116:117], v[114:115], 0, s[20:21]
	global_load_dwordx2 v[64:65], v[116:117], off
	v_lshl_add_u64 v[118:119], v[116:117], 0, s[20:21]
	global_load_dwordx2 v[66:67], v[118:119], off
	v_lshl_add_u64 v[120:121], v[118:119], 0, s[20:21]
	global_load_dwordx2 v[68:69], v[120:121], off
	v_lshl_add_u64 v[122:123], v[120:121], 0, s[20:21]
	global_load_dwordx2 v[70:71], v[122:123], off
	v_lshl_add_u64 v[108:109], v[0:1], 0, s[6:7]
	s_add_u32 s6, s6, 0x30000
	s_addc_u32 s7, s7, 0
	global_load_dwordx2 v[92:93], v[108:109], off
	v_lshl_add_u64 v[110:111], v[108:109], 0, s[20:21]
	global_load_dwordx2 v[94:95], v[110:111], off
	v_lshl_add_u64 v[112:113], v[110:111], 0, s[20:21]
	global_load_dwordx2 v[96:97], v[112:113], off
	v_lshl_add_u64 v[114:115], v[112:113], 0, s[20:21]
	global_load_dwordx2 v[98:99], v[114:115], off
	v_lshl_add_u64 v[116:117], v[114:115], 0, s[20:21]
	global_load_dwordx2 v[100:101], v[116:117], off
	v_lshl_add_u64 v[118:119], v[116:117], 0, s[20:21]
	global_load_dwordx2 v[102:103], v[118:119], off
	v_lshl_add_u64 v[120:121], v[118:119], 0, s[20:21]
	global_load_dwordx2 v[104:105], v[120:121], off
	v_lshl_add_u64 v[122:123], v[120:121], 0, s[20:21]
	global_load_dwordx2 v[106:107], v[122:123], off
	v_mov_b32_e32 v52, s9
	s_add_i32 s9, s9, 32
	ds_read_b128 v[16:19], v52
	ds_read_b128 v[20:23], v52 offset:16
	ds_read_b128 v[24:27], v52 offset:4096
	ds_read_b128 v[28:31], v52 offset:4112
	ds_read_b128 v[32:35], v52 offset:8192
	ds_read_b128 v[36:39], v52 offset:8208
	ds_read_b128 v[40:43], v52 offset:12288
	ds_read_b128 v[44:47], v52 offset:12304
	ds_read_b128 v[48:51], v52 offset:16384
	ds_read_b128 v[52:55], v52 offset:16400
	s_waitcnt lgkmcnt(0)
	v_mov_b32_e32 v72, v19
	v_mov_b32_e32 v74, v27
	v_mov_b32_e32 v76, v35
	v_mov_b32_e32 v78, v43
	v_mov_b32_e32 v80, v51
	v_mov_b32_e32 v82, v23
	v_mov_b32_e32 v84, v31
	v_mov_b32_e32 v86, v39
	v_mov_b32_e32 v88, v47
	v_mov_b32_e32 v90, v55
	s_waitcnt vmcnt(15)
	v_pk_fma_f32 v[6:7], v[56:57], v[16:17], v[6:7] op_sel_hi:[1,0,1]
	v_pk_fma_f32 v[8:9], v[56:57], v[24:25], v[8:9] op_sel_hi:[1,0,1]
	v_pk_fma_f32 v[10:11], v[56:57], v[32:33], v[10:11] op_sel_hi:[1,0,1]
	v_pk_fma_f32 v[12:13], v[56:57], v[40:41], v[12:13] op_sel_hi:[1,0,1]
	v_pk_fma_f32 v[4:5], v[56:57], v[48:49], v[4:5] op_sel_hi:[1,0,1]
	s_waitcnt vmcnt(14)
	v_pk_fma_f32 v[6:7], v[58:59], v[16:17], v[6:7] op_sel:[0,1,0]
	v_pk_fma_f32 v[8:9], v[58:59], v[24:25], v[8:9] op_sel:[0,1,0]
	v_pk_fma_f32 v[10:11], v[58:59], v[32:33], v[10:11] op_sel:[0,1,0]
	v_pk_fma_f32 v[12:13], v[58:59], v[40:41], v[12:13] op_sel:[0,1,0]
	v_pk_fma_f32 v[4:5], v[58:59], v[48:49], v[4:5] op_sel:[0,1,0]
	s_waitcnt vmcnt(13)
	v_pk_fma_f32 v[6:7], v[60:61], v[18:19], v[6:7] op_sel_hi:[1,0,1]
	v_pk_fma_f32 v[8:9], v[60:61], v[26:27], v[8:9] op_sel_hi:[1,0,1]
	v_pk_fma_f32 v[10:11], v[60:61], v[34:35], v[10:11] op_sel_hi:[1,0,1]
	v_pk_fma_f32 v[12:13], v[60:61], v[42:43], v[12:13] op_sel_hi:[1,0,1]
	v_pk_fma_f32 v[4:5], v[60:61], v[50:51], v[4:5] op_sel_hi:[1,0,1]
	s_waitcnt vmcnt(12)
	v_pk_fma_f32 v[6:7], v[62:63], v[72:73], v[6:7] op_sel_hi:[1,0,1]
	v_pk_fma_f32 v[8:9], v[62:63], v[74:75], v[8:9] op_sel_hi:[1,0,1]
	v_pk_fma_f32 v[10:11], v[62:63], v[76:77], v[10:11] op_sel_hi:[1,0,1]
	v_pk_fma_f32 v[12:13], v[62:63], v[78:79], v[12:13] op_sel_hi:[1,0,1]
	v_pk_fma_f32 v[4:5], v[62:63], v[80:81], v[4:5] op_sel_hi:[1,0,1]
	s_waitcnt vmcnt(11)
	v_pk_fma_f32 v[6:7], v[64:65], v[20:21], v[6:7] op_sel_hi:[1,0,1]
	v_pk_fma_f32 v[8:9], v[64:65], v[28:29], v[8:9] op_sel_hi:[1,0,1]
	v_pk_fma_f32 v[10:11], v[64:65], v[36:37], v[10:11] op_sel_hi:[1,0,1]
	v_pk_fma_f32 v[12:13], v[64:65], v[44:45], v[12:13] op_sel_hi:[1,0,1]
	v_pk_fma_f32 v[4:5], v[64:65], v[52:53], v[4:5] op_sel_hi:[1,0,1]
	s_waitcnt vmcnt(10)
	v_pk_fma_f32 v[6:7], v[66:67], v[20:21], v[6:7] op_sel:[0,1,0]
	v_pk_fma_f32 v[8:9], v[66:67], v[28:29], v[8:9] op_sel:[0,1,0]
	v_pk_fma_f32 v[10:11], v[66:67], v[36:37], v[10:11] op_sel:[0,1,0]
	v_pk_fma_f32 v[12:13], v[66:67], v[44:45], v[12:13] op_sel:[0,1,0]
	v_pk_fma_f32 v[4:5], v[66:67], v[52:53], v[4:5] op_sel:[0,1,0]
	s_waitcnt vmcnt(9)
	v_pk_fma_f32 v[6:7], v[68:69], v[22:23], v[6:7] op_sel_hi:[1,0,1]
	v_pk_fma_f32 v[8:9], v[68:69], v[30:31], v[8:9] op_sel_hi:[1,0,1]
	v_pk_fma_f32 v[10:11], v[68:69], v[38:39], v[10:11] op_sel_hi:[1,0,1]
	v_pk_fma_f32 v[12:13], v[68:69], v[46:47], v[12:13] op_sel_hi:[1,0,1]
	v_pk_fma_f32 v[4:5], v[68:69], v[54:55], v[4:5] op_sel_hi:[1,0,1]
	s_waitcnt vmcnt(8)
; __device__ __forceinline__ void prologue_phase(const Args& a, LAS unsigned char* lds) {
;     ...
;         const float* wp = a.ada_w + ((size_t)l * DM + 128 * w) * 6144 + j;
; #pragma unroll 8
;         for (int kk = 0; kk < 128; ++kk) { const int k = 128 * w + kk; const f32x2_t wv = *(const f32x2_t*)(wp + (size_t)kk * 6144);
; #pragma unroll
;             for (int s = 0; s < 5; ++s) { const float sv = sil[s * DM + k]; acc[s][0] += sv * wv.x; acc[s][1] += sv * wv.y; } }
	v_pk_fma_f32 v[6:7], v[70:71], v[82:83], v[6:7] op_sel_hi:[1,0,1]
	v_pk_fma_f32 v[8:9], v[70:71], v[84:85], v[8:9] op_sel_hi:[1,0,1]
	v_pk_fma_f32 v[10:11], v[70:71], v[86:87], v[10:11] op_sel_hi:[1,0,1]
	v_pk_fma_f32 v[12:13], v[70:71], v[88:89], v[12:13] op_sel_hi:[1,0,1]
	v_pk_fma_f32 v[4:5], v[70:71], v[90:91], v[4:5] op_sel_hi:[1,0,1]
	v_lshl_add_u64 v[108:109], v[0:1], 0, s[6:7]
	s_add_u32 s6, s6, 0x30000
	s_addc_u32 s7, s7, 0
	global_load_dwordx2 v[56:57], v[108:109], off
	v_lshl_add_u64 v[110:111], v[108:109], 0, s[20:21]
	global_load_dwordx2 v[58:59], v[110:111], off
	v_lshl_add_u64 v[112:113], v[110:111], 0, s[20:21]
	global_load_dwordx2 v[60:61], v[112:113], off
	v_lshl_add_u64 v[114:115], v[112:113], 0, s[20:21]
	global_load_dwordx2 v[62:63], v[114:115], off
	v_lshl_add_u64 v[116:117], v[114:115], 0, s[20:21]
	global_load_dwordx2 v[64:65], v[116:117], off
	v_lshl_add_u64 v[118:119], v[116:117], 0, s[20:21]
	global_load_dwordx2 v[66:67], v[118:119], off
	v_lshl_add_u64 v[120:121], v[118:119], 0, s[20:21]
	global_load_dwordx2 v[68:69], v[120:121], off
	v_lshl_add_u64 v[122:123], v[120:121], 0, s[20:21]
	global_load_dwordx2 v[70:71], v[122:123], off
	v_mov_b32_e32 v52, s9
	s_add_i32 s9, s9, 32
	ds_read_b128 v[16:19], v52
	ds_read_b128 v[20:23], v52 offset:16
	ds_read_b128 v[24:27], v52 offset:4096
	ds_read_b128 v[28:31], v52 offset:4112
	ds_read_b128 v[32:35], v52 offset:8192
	ds_read_b128 v[36:39], v52 offset:8208
	ds_read_b128 v[40:43], v52 offset:12288
	ds_read_b128 v[44:47], v52 offset:12304
	ds_read_b128 v[48:51], v52 offset:16384
	ds_read_b128 v[52:55], v52 offset:16400
	s_waitcnt lgkmcnt(0)
	v_mov_b32_e32 v72, v19
	v_mov_b32_e32 v74, v27
	v_mov_b32_e32 v76, v35
	v_mov_b32_e32 v78, v43
	v_mov_b32_e32 v80, v51
	v_mov_b32_e32 v82, v23
	v_mov_b32_e32 v84, v31
	v_mov_b32_e32 v86, v39
	v_mov_b32_e32 v88, v47
	v_mov_b32_e32 v90, v55
	s_waitcnt vmcnt(15)
	v_pk_fma_f32 v[6:7], v[92:93], v[16:17], v[6:7] op_sel_hi:[1,0,1]
	v_pk_fma_f32 v[8:9], v[92:93], v[24:25], v[8:9] op_sel_hi:[1,0,1]
	v_pk_fma_f32 v[10:11], v[92:93], v[32:33], v[10:11] op_sel_hi:[1,0,1]
	v_pk_fma_f32 v[12:13], v[92:93], v[40:41], v[12:13] op_sel_hi:[1,0,1]
	v_pk_fma_f32 v[4:5], v[92:93], v[48:49], v[4:5] op_sel_hi:[1,0,1]
	s_waitcnt vmcnt(14)
	v_pk_fma_f32 v[6:7], v[94:95], v[16:17], v[6:7] op_sel:[0,1,0]
	v_pk_fma_f32 v[8:9], v[94:95], v[24:25], v[8:9] op_sel:[0,1,0]
	v_pk_fma_f32 v[10:11], v[94:95], v[32:33], v[10:11] op_sel:[0,1,0]
	v_pk_fma_f32 v[12:13], v[94:95], v[40:41], v[12:13] op_sel:[0,1,0]
	v_pk_fma_f32 v[4:5], v[94:95], v[48:49], v[4:5] op_sel:[0,1,0]
	s_waitcnt vmcnt(13)
	v_pk_fma_f32 v[6:7], v[96:97], v[18:19], v[6:7] op_sel_hi:[1,0,1]
	v_pk_fma_f32 v[8:9], v[96:97], v[26:27], v[8:9] op_sel_hi:[1,0,1]
	v_pk_fma_f32 v[10:11], v[96:97], v[34:35], v[10:11] op_sel_hi:[1,0,1]
	v_pk_fma_f32 v[12:13], v[96:97], v[42:43], v[12:13] op_sel_hi:[1,0,1]
	v_pk_fma_f32 v[4:5], v[96:97], v[50:51], v[4:5] op_sel_hi:[1,0,1]
	s_waitcnt vmcnt(12)
	v_pk_fma_f32 v[6:7], v[98:99], v[72:73], v[6:7] op_sel_hi:[1,0,1]
	v_pk_fma_f32 v[8:9], v[98:99], v[74:75], v[8:9] op_sel_hi:[1,0,1]
	v_pk_fma_f32 v[10:11], v[98:99], v[76:77], v[10:11] op_sel_hi:[1,0,1]
	v_pk_fma_f32 v[12:13], v[98:99], v[78:79], v[12:13] op_sel_hi:[1,0,1]
	v_pk_fma_f32 v[4:5], v[98:99], v[80:81], v[4:5] op_sel_hi:[1,0,1]
	s_waitcnt vmcnt(11)
	v_pk_fma_f32 v[6:7], v[100:101], v[20:21], v[6:7] op_sel_hi:[1,0,1]
	v_pk_fma_f32 v[8:9], v[100:101], v[28:29], v[8:9] op_sel_hi:[1,0,1]
	v_pk_fma_f32 v[10:11], v[100:101], v[36:37], v[10:11] op_sel_hi:[1,0,1]
	v_pk_fma_f32 v[12:13], v[100:101], v[44:45], v[12:13] op_sel_hi:[1,0,1]
	v_pk_fma_f32 v[4:5], v[100:101], v[52:53], v[4:5] op_sel_hi:[1,0,1]
	s_waitcnt vmcnt(10)
	v_pk_fma_f32 v[6:7], v[102:103], v[20:21], v[6:7] op_sel:[0,1,0]
	v_pk_fma_f32 v[8:9], v[102:103], v[28:29], v[8:9] op_sel:[0,1,0]
	v_pk_fma_f32 v[10:11], v[102:103], v[36:37], v[10:11] op_sel:[0,1,0]
	v_pk_fma_f32 v[12:13], v[102:103], v[44:45], v[12:13] op_sel:[0,1,0]
	v_pk_fma_f32 v[4:5], v[102:103], v[52:53], v[4:5] op_sel:[0,1,0]
	s_waitcnt vmcnt(9)
	v_pk_fma_f32 v[6:7], v[104:105], v[22:23], v[6:7] op_sel_hi:[1,0,1]
	v_pk_fma_f32 v[8:9], v[104:105], v[30:31], v[8:9] op_sel_hi:[1,0,1]
	v_pk_fma_f32 v[10:11], v[104:105], v[38:39], v[10:11] op_sel_hi:[1,0,1]
	v_pk_fma_f32 v[12:13], v[104:105], v[46:47], v[12:13] op_sel_hi:[1,0,1]
	v_pk_fma_f32 v[4:5], v[104:105], v[54:55], v[4:5] op_sel_hi:[1,0,1]
	s_waitcnt vmcnt(8)
	v_pk_fma_f32 v[6:7], v[106:107], v[82:83], v[6:7] op_sel_hi:[1,0,1]
	v_pk_fma_f32 v[8:9], v[106:107], v[84:85], v[8:9] op_sel_hi:[1,0,1]
	v_pk_fma_f32 v[10:11], v[106:107], v[86:87], v[10:11] op_sel_hi:[1,0,1]
	v_pk_fma_f32 v[12:13], v[106:107], v[88:89], v[12:13] op_sel_hi:[1,0,1]
	v_pk_fma_f32 v[4:5], v[106:107], v[90:91], v[4:5] op_sel_hi:[1,0,1]
	v_lshl_add_u64 v[108:109], v[0:1], 0, s[6:7]
	s_add_u32 s6, s6, 0x30000
	s_addc_u32 s7, s7, 0
	global_load_dwordx2 v[92:93], v[108:109], off
	v_lshl_add_u64 v[110:111], v[108:109], 0, s[20:21]
	global_load_dwordx2 v[94:95], v[110:111], off
	v_lshl_add_u64 v[112:113], v[110:111], 0, s[20:21]
	global_load_dwordx2 v[96:97], v[112:113], off
	v_lshl_add_u64 v[114:115], v[112:113], 0, s[20:21]
	global_load_dwordx2 v[98:99], v[114:115], off
	v_lshl_add_u64 v[116:117], v[114:115], 0, s[20:21]
	global_load_dwordx2 v[100:101], v[116:117], off
	v_lshl_add_u64 v[118:119], v[116:117], 0, s[20:21]
	global_load_dwordx2 v[102:103], v[118:119], off
	v_lshl_add_u64 v[120:121], v[118:119], 0, s[20:21]
	global_load_dwordx2 v[104:105], v[120:121], off
	v_lshl_add_u64 v[122:123], v[120:121], 0, s[20:21]
	global_load_dwordx2 v[106:107], v[122:123], off
	v_mov_b32_e32 v52, s9
	s_add_i32 s9, s9, 32
	ds_read_b128 v[16:19], v52
	ds_read_b128 v[20:23], v52 offset:16
	ds_read_b128 v[24:27], v52 offset:4096
	ds_read_b128 v[28:31], v52 offset:4112
	ds_read_b128 v[32:35], v52 offset:8192
	ds_read_b128 v[36:39], v52 offset:8208
	ds_read_b128 v[40:43], v52 offset:12288
	ds_read_b128 v[44:47], v52 offset:12304
	ds_read_b128 v[48:51], v52 offset:16384
	ds_read_b128 v[52:55], v52 offset:16400
	s_waitcnt lgkmcnt(0)
; __device__ __forceinline__ void prologue_phase(const Args& a, LAS unsigned char* lds) {
;     ...
;         const float* wp = a.ada_w + ((size_t)l * DM + 128 * w) * 6144 + j;
; #pragma unroll 8
;         for (int kk = 0; kk < 128; ++kk) { const int k = 128 * w + kk; const f32x2_t wv = *(const f32x2_t*)(wp + (size_t)kk * 6144);
; #pragma unroll
;             for (int s = 0; s < 5; ++s) { const float sv = sil[s * DM + k]; acc[s][0] += sv * wv.x; acc[s][1] += sv * wv.y; } }
	v_mov_b32_e32 v72, v19
	v_mov_b32_e32 v74, v27
	v_mov_b32_e32 v76, v35
	v_mov_b32_e32 v78, v43
	v_mov_b32_e32 v80, v51
	v_mov_b32_e32 v82, v23
	v_mov_b32_e32 v84, v31
	v_mov_b32_e32 v86, v39
	v_mov_b32_e32 v88, v47
	v_mov_b32_e32 v90, v55
	s_waitcnt vmcnt(15)
	v_pk_fma_f32 v[6:7], v[56:57], v[16:17], v[6:7] op_sel_hi:[1,0,1]
	v_pk_fma_f32 v[8:9], v[56:57], v[24:25], v[8:9] op_sel_hi:[1,0,1]
	v_pk_fma_f32 v[10:11], v[56:57], v[32:33], v[10:11] op_sel_hi:[1,0,1]
	v_pk_fma_f32 v[12:13], v[56:57], v[40:41], v[12:13] op_sel_hi:[1,0,1]
	v_pk_fma_f32 v[4:5], v[56:57], v[48:49], v[4:5] op_sel_hi:[1,0,1]
	s_waitcnt vmcnt(14)
	v_pk_fma_f32 v[6:7], v[58:59], v[16:17], v[6:7] op_sel:[0,1,0]
	v_pk_fma_f32 v[8:9], v[58:59], v[24:25], v[8:9] op_sel:[0,1,0]
	v_pk_fma_f32 v[10:11], v[58:59], v[32:33], v[10:11] op_sel:[0,1,0]
	v_pk_fma_f32 v[12:13], v[58:59], v[40:41], v[12:13] op_sel:[0,1,0]
	v_pk_fma_f32 v[4:5], v[58:59], v[48:49], v[4:5] op_sel:[0,1,0]
	s_waitcnt vmcnt(13)
	v_pk_fma_f32 v[6:7], v[60:61], v[18:19], v[6:7] op_sel_hi:[1,0,1]
	v_pk_fma_f32 v[8:9], v[60:61], v[26:27], v[8:9] op_sel_hi:[1,0,1]
	v_pk_fma_f32 v[10:11], v[60:61], v[34:35], v[10:11] op_sel_hi:[1,0,1]
	v_pk_fma_f32 v[12:13], v[60:61], v[42:43], v[12:13] op_sel_hi:[1,0,1]
	v_pk_fma_f32 v[4:5], v[60:61], v[50:51], v[4:5] op_sel_hi:[1,0,1]
	s_waitcnt vmcnt(12)
	v_pk_fma_f32 v[6:7], v[62:63], v[72:73], v[6:7] op_sel_hi:[1,0,1]
	v_pk_fma_f32 v[8:9], v[62:63], v[74:75], v[8:9] op_sel_hi:[1,0,1]
	v_pk_fma_f32 v[10:11], v[62:63], v[76:77], v[10:11] op_sel_hi:[1,0,1]
	v_pk_fma_f32 v[12:13], v[62:63], v[78:79], v[12:13] op_sel_hi:[1,0,1]
	v_pk_fma_f32 v[4:5], v[62:63], v[80:81], v[4:5] op_sel_hi:[1,0,1]
	s_waitcnt vmcnt(11)
	v_pk_fma_f32 v[6:7], v[64:65], v[20:21], v[6:7] op_sel_hi:[1,0,1]
	v_pk_fma_f32 v[8:9], v[64:65], v[28:29], v[8:9] op_sel_hi:[1,0,1]
	v_pk_fma_f32 v[10:11], v[64:65], v[36:37], v[10:11] op_sel_hi:[1,0,1]
	v_pk_fma_f32 v[12:13], v[64:65], v[44:45], v[12:13] op_sel_hi:[1,0,1]
	v_pk_fma_f32 v[4:5], v[64:65], v[52:53], v[4:5] op_sel_hi:[1,0,1]
	s_waitcnt vmcnt(10)
	v_pk_fma_f32 v[6:7], v[66:67], v[20:21], v[6:7] op_sel:[0,1,0]
	v_pk_fma_f32 v[8:9], v[66:67], v[28:29], v[8:9] op_sel:[0,1,0]
	v_pk_fma_f32 v[10:11], v[66:67], v[36:37], v[10:11] op_sel:[0,1,0]
	v_pk_fma_f32 v[12:13], v[66:67], v[44:45], v[12:13] op_sel:[0,1,0]
	v_pk_fma_f32 v[4:5], v[66:67], v[52:53], v[4:5] op_sel:[0,1,0]
	s_waitcnt vmcnt(9)
	v_pk_fma_f32 v[6:7], v[68:69], v[22:23], v[6:7] op_sel_hi:[1,0,1]
	v_pk_fma_f32 v[8:9], v[68:69], v[30:31], v[8:9] op_sel_hi:[1,0,1]
	v_pk_fma_f32 v[10:11], v[68:69], v[38:39], v[10:11] op_sel_hi:[1,0,1]
	v_pk_fma_f32 v[12:13], v[68:69], v[46:47], v[12:13] op_sel_hi:[1,0,1]
	v_pk_fma_f32 v[4:5], v[68:69], v[54:55], v[4:5] op_sel_hi:[1,0,1]
	s_waitcnt vmcnt(8)
	v_pk_fma_f32 v[6:7], v[70:71], v[82:83], v[6:7] op_sel_hi:[1,0,1]
	v_pk_fma_f32 v[8:9], v[70:71], v[84:85], v[8:9] op_sel_hi:[1,0,1]
	v_pk_fma_f32 v[10:11], v[70:71], v[86:87], v[10:11] op_sel_hi:[1,0,1]
	v_pk_fma_f32 v[12:13], v[70:71], v[88:89], v[12:13] op_sel_hi:[1,0,1]
	v_pk_fma_f32 v[4:5], v[70:71], v[90:91], v[4:5] op_sel_hi:[1,0,1]
	v_lshl_add_u64 v[108:109], v[0:1], 0, s[6:7]
	s_add_u32 s6, s6, 0x30000
	s_addc_u32 s7, s7, 0
	global_load_dwordx2 v[56:57], v[108:109], off
	v_lshl_add_u64 v[110:111], v[108:109], 0, s[20:21]
	global_load_dwordx2 v[58:59], v[110:111], off
	v_lshl_add_u64 v[112:113], v[110:111], 0, s[20:21]
	global_load_dwordx2 v[60:61], v[112:113], off
	v_lshl_add_u64 v[114:115], v[112:113], 0, s[20:21]
	global_load_dwordx2 v[62:63], v[114:115], off
	v_lshl_add_u64 v[116:117], v[114:115], 0, s[20:21]
	global_load_dwordx2 v[64:65], v[116:117], off
	v_lshl_add_u64 v[118:119], v[116:117], 0, s[20:21]
	global_load_dwordx2 v[66:67], v[118:119], off
	v_lshl_add_u64 v[120:121], v[118:119], 0, s[20:21]
	global_load_dwordx2 v[68:69], v[120:121], off
	v_lshl_add_u64 v[122:123], v[120:121], 0, s[20:21]
	global_load_dwordx2 v[70:71], v[122:123], off
	v_mov_b32_e32 v52, s9
	s_add_i32 s9, s9, 32
	ds_read_b128 v[16:19], v52
	ds_read_b128 v[20:23], v52 offset:16
	ds_read_b128 v[24:27], v52 offset:4096
	ds_read_b128 v[28:31], v52 offset:4112
	ds_read_b128 v[32:35], v52 offset:8192
	ds_read_b128 v[36:39], v52 offset:8208
	ds_read_b128 v[40:43], v52 offset:12288
	ds_read_b128 v[44:47], v52 offset:12304
	ds_read_b128 v[48:51], v52 offset:16384
	ds_read_b128 v[52:55], v52 offset:16400
	s_waitcnt lgkmcnt(0)
	v_mov_b32_e32 v72, v19
	v_mov_b32_e32 v74, v27
	v_mov_b32_e32 v76, v35
	v_mov_b32_e32 v78, v43
	v_mov_b32_e32 v80, v51
	v_mov_b32_e32 v82, v23
	v_mov_b32_e32 v84, v31
	v_mov_b32_e32 v86, v39
	v_mov_b32_e32 v88, v47
	v_mov_b32_e32 v90, v55
	s_waitcnt vmcnt(15)
	v_pk_fma_f32 v[6:7], v[92:93], v[16:17], v[6:7] op_sel_hi:[1,0,1]
	v_pk_fma_f32 v[8:9], v[92:93], v[24:25], v[8:9] op_sel_hi:[1,0,1]
	v_pk_fma_f32 v[10:11], v[92:93], v[32:33], v[10:11] op_sel_hi:[1,0,1]
	v_pk_fma_f32 v[12:13], v[92:93], v[40:41], v[12:13] op_sel_hi:[1,0,1]
	v_pk_fma_f32 v[4:5], v[92:93], v[48:49], v[4:5] op_sel_hi:[1,0,1]
	s_waitcnt vmcnt(14)
	v_pk_fma_f32 v[6:7], v[94:95], v[16:17], v[6:7] op_sel:[0,1,0]
	v_pk_fma_f32 v[8:9], v[94:95], v[24:25], v[8:9] op_sel:[0,1,0]
	v_pk_fma_f32 v[10:11], v[94:95], v[32:33], v[10:11] op_sel:[0,1,0]
	v_pk_fma_f32 v[12:13], v[94:95], v[40:41], v[12:13] op_sel:[0,1,0]
	v_pk_fma_f32 v[4:5], v[94:95], v[48:49], v[4:5] op_sel:[0,1,0]
	s_waitcnt vmcnt(13)
	v_pk_fma_f32 v[6:7], v[96:97], v[18:19], v[6:7] op_sel_hi:[1,0,1]
	v_pk_fma_f32 v[8:9], v[96:97], v[26:27], v[8:9] op_sel_hi:[1,0,1]
	v_pk_fma_f32 v[10:11], v[96:97], v[34:35], v[10:11] op_sel_hi:[1,0,1]
	v_pk_fma_f32 v[12:13], v[96:97], v[42:43], v[12:13] op_sel_hi:[1,0,1]
	v_pk_fma_f32 v[4:5], v[96:97], v[50:51], v[4:5] op_sel_hi:[1,0,1]
	s_waitcnt vmcnt(12)
; __device__ __forceinline__ void prologue_phase(const Args& a, LAS unsigned char* lds) {
;     ...
;         const float* wp = a.ada_w + ((size_t)l * DM + 128 * w) * 6144 + j;
; #pragma unroll 8
;         for (int kk = 0; kk < 128; ++kk) { const int k = 128 * w + kk; const f32x2_t wv = *(const f32x2_t*)(wp + (size_t)kk * 6144);
; #pragma unroll
;             for (int s = 0; s < 5; ++s) { const float sv = sil[s * DM + k]; acc[s][0] += sv * wv.x; acc[s][1] += sv * wv.y; } }
	v_pk_fma_f32 v[6:7], v[98:99], v[72:73], v[6:7] op_sel_hi:[1,0,1]
	v_pk_fma_f32 v[8:9], v[98:99], v[74:75], v[8:9] op_sel_hi:[1,0,1]
	v_pk_fma_f32 v[10:11], v[98:99], v[76:77], v[10:11] op_sel_hi:[1,0,1]
	v_pk_fma_f32 v[12:13], v[98:99], v[78:79], v[12:13] op_sel_hi:[1,0,1]
	v_pk_fma_f32 v[4:5], v[98:99], v[80:81], v[4:5] op_sel_hi:[1,0,1]
	s_waitcnt vmcnt(11)
	v_pk_fma_f32 v[6:7], v[100:101], v[20:21], v[6:7] op_sel_hi:[1,0,1]
	v_pk_fma_f32 v[8:9], v[100:101], v[28:29], v[8:9] op_sel_hi:[1,0,1]
	v_pk_fma_f32 v[10:11], v[100:101], v[36:37], v[10:11] op_sel_hi:[1,0,1]
	v_pk_fma_f32 v[12:13], v[100:101], v[44:45], v[12:13] op_sel_hi:[1,0,1]
	v_pk_fma_f32 v[4:5], v[100:101], v[52:53], v[4:5] op_sel_hi:[1,0,1]
	s_waitcnt vmcnt(10)
	v_pk_fma_f32 v[6:7], v[102:103], v[20:21], v[6:7] op_sel:[0,1,0]
	v_pk_fma_f32 v[8:9], v[102:103], v[28:29], v[8:9] op_sel:[0,1,0]
	v_pk_fma_f32 v[10:11], v[102:103], v[36:37], v[10:11] op_sel:[0,1,0]
	v_pk_fma_f32 v[12:13], v[102:103], v[44:45], v[12:13] op_sel:[0,1,0]
	v_pk_fma_f32 v[4:5], v[102:103], v[52:53], v[4:5] op_sel:[0,1,0]
	s_waitcnt vmcnt(9)
	v_pk_fma_f32 v[6:7], v[104:105], v[22:23], v[6:7] op_sel_hi:[1,0,1]
	v_pk_fma_f32 v[8:9], v[104:105], v[30:31], v[8:9] op_sel_hi:[1,0,1]
	v_pk_fma_f32 v[10:11], v[104:105], v[38:39], v[10:11] op_sel_hi:[1,0,1]
	v_pk_fma_f32 v[12:13], v[104:105], v[46:47], v[12:13] op_sel_hi:[1,0,1]
	v_pk_fma_f32 v[4:5], v[104:105], v[54:55], v[4:5] op_sel_hi:[1,0,1]
	s_waitcnt vmcnt(8)
	v_pk_fma_f32 v[6:7], v[106:107], v[82:83], v[6:7] op_sel_hi:[1,0,1]
	v_pk_fma_f32 v[8:9], v[106:107], v[84:85], v[8:9] op_sel_hi:[1,0,1]
	v_pk_fma_f32 v[10:11], v[106:107], v[86:87], v[10:11] op_sel_hi:[1,0,1]
	v_pk_fma_f32 v[12:13], v[106:107], v[88:89], v[12:13] op_sel_hi:[1,0,1]
	v_pk_fma_f32 v[4:5], v[106:107], v[90:91], v[4:5] op_sel_hi:[1,0,1]
	v_lshl_add_u64 v[108:109], v[0:1], 0, s[6:7]
	s_add_u32 s6, s6, 0x30000
	s_addc_u32 s7, s7, 0
	global_load_dwordx2 v[92:93], v[108:109], off
	v_lshl_add_u64 v[110:111], v[108:109], 0, s[20:21]
	global_load_dwordx2 v[94:95], v[110:111], off
	v_lshl_add_u64 v[112:113], v[110:111], 0, s[20:21]
	global_load_dwordx2 v[96:97], v[112:113], off
	v_lshl_add_u64 v[114:115], v[112:113], 0, s[20:21]
	global_load_dwordx2 v[98:99], v[114:115], off
	v_lshl_add_u64 v[116:117], v[114:115], 0, s[20:21]
	global_load_dwordx2 v[100:101], v[116:117], off
	v_lshl_add_u64 v[118:119], v[116:117], 0, s[20:21]
	global_load_dwordx2 v[102:103], v[118:119], off
	v_lshl_add_u64 v[120:121], v[118:119], 0, s[20:21]
	global_load_dwordx2 v[104:105], v[120:121], off
	v_lshl_add_u64 v[122:123], v[120:121], 0, s[20:21]
	global_load_dwordx2 v[106:107], v[122:123], off
	v_mov_b32_e32 v52, s9
	s_add_i32 s9, s9, 32
	ds_read_b128 v[16:19], v52
	ds_read_b128 v[20:23], v52 offset:16
	ds_read_b128 v[24:27], v52 offset:4096
	ds_read_b128 v[28:31], v52 offset:4112
	ds_read_b128 v[32:35], v52 offset:8192
	ds_read_b128 v[36:39], v52 offset:8208
	ds_read_b128 v[40:43], v52 offset:12288
	ds_read_b128 v[44:47], v52 offset:12304
	ds_read_b128 v[48:51], v52 offset:16384
	ds_read_b128 v[52:55], v52 offset:16400
	s_waitcnt lgkmcnt(0)
	v_mov_b32_e32 v72, v19
	v_mov_b32_e32 v74, v27
	v_mov_b32_e32 v76, v35
	v_mov_b32_e32 v78, v43
	v_mov_b32_e32 v80, v51
	v_mov_b32_e32 v82, v23
	v_mov_b32_e32 v84, v31
	v_mov_b32_e32 v86, v39
	v_mov_b32_e32 v88, v47
	v_mov_b32_e32 v90, v55
	s_waitcnt vmcnt(15)
	v_pk_fma_f32 v[6:7], v[56:57], v[16:17], v[6:7] op_sel_hi:[1,0,1]
	v_pk_fma_f32 v[8:9], v[56:57], v[24:25], v[8:9] op_sel_hi:[1,0,1]
	v_pk_fma_f32 v[10:11], v[56:57], v[32:33], v[10:11] op_sel_hi:[1,0,1]
	v_pk_fma_f32 v[12:13], v[56:57], v[40:41], v[12:13] op_sel_hi:[1,0,1]
	v_pk_fma_f32 v[4:5], v[56:57], v[48:49], v[4:5] op_sel_hi:[1,0,1]
	s_waitcnt vmcnt(14)
	v_pk_fma_f32 v[6:7], v[58:59], v[16:17], v[6:7] op_sel:[0,1,0]
	v_pk_fma_f32 v[8:9], v[58:59], v[24:25], v[8:9] op_sel:[0,1,0]
	v_pk_fma_f32 v[10:11], v[58:59], v[32:33], v[10:11] op_sel:[0,1,0]
	v_pk_fma_f32 v[12:13], v[58:59], v[40:41], v[12:13] op_sel:[0,1,0]
	v_pk_fma_f32 v[4:5], v[58:59], v[48:49], v[4:5] op_sel:[0,1,0]
	s_waitcnt vmcnt(13)
	v_pk_fma_f32 v[6:7], v[60:61], v[18:19], v[6:7] op_sel_hi:[1,0,1]
	v_pk_fma_f32 v[8:9], v[60:61], v[26:27], v[8:9] op_sel_hi:[1,0,1]
	v_pk_fma_f32 v[10:11], v[60:61], v[34:35], v[10:11] op_sel_hi:[1,0,1]
	v_pk_fma_f32 v[12:13], v[60:61], v[42:43], v[12:13] op_sel_hi:[1,0,1]
	v_pk_fma_f32 v[4:5], v[60:61], v[50:51], v[4:5] op_sel_hi:[1,0,1]
	s_waitcnt vmcnt(12)
	v_pk_fma_f32 v[6:7], v[62:63], v[72:73], v[6:7] op_sel_hi:[1,0,1]
	v_pk_fma_f32 v[8:9], v[62:63], v[74:75], v[8:9] op_sel_hi:[1,0,1]
	v_pk_fma_f32 v[10:11], v[62:63], v[76:77], v[10:11] op_sel_hi:[1,0,1]
	v_pk_fma_f32 v[12:13], v[62:63], v[78:79], v[12:13] op_sel_hi:[1,0,1]
	v_pk_fma_f32 v[4:5], v[62:63], v[80:81], v[4:5] op_sel_hi:[1,0,1]
	s_waitcnt vmcnt(11)
	v_pk_fma_f32 v[6:7], v[64:65], v[20:21], v[6:7] op_sel_hi:[1,0,1]
	v_pk_fma_f32 v[8:9], v[64:65], v[28:29], v[8:9] op_sel_hi:[1,0,1]
	v_pk_fma_f32 v[10:11], v[64:65], v[36:37], v[10:11] op_sel_hi:[1,0,1]
	v_pk_fma_f32 v[12:13], v[64:65], v[44:45], v[12:13] op_sel_hi:[1,0,1]
	v_pk_fma_f32 v[4:5], v[64:65], v[52:53], v[4:5] op_sel_hi:[1,0,1]
	s_waitcnt vmcnt(10)
	v_pk_fma_f32 v[6:7], v[66:67], v[20:21], v[6:7] op_sel:[0,1,0]
	v_pk_fma_f32 v[8:9], v[66:67], v[28:29], v[8:9] op_sel:[0,1,0]
	v_pk_fma_f32 v[10:11], v[66:67], v[36:37], v[10:11] op_sel:[0,1,0]
	v_pk_fma_f32 v[12:13], v[66:67], v[44:45], v[12:13] op_sel:[0,1,0]
	v_pk_fma_f32 v[4:5], v[66:67], v[52:53], v[4:5] op_sel:[0,1,0]
	s_waitcnt vmcnt(9)
; __device__ __forceinline__ void prologue_phase(const Args& a, LAS unsigned char* lds) {
;     ...
;         const float* wp = a.ada_w + ((size_t)l * DM + 128 * w) * 6144 + j;
; #pragma unroll 8
;         for (int kk = 0; kk < 128; ++kk) { const int k = 128 * w + kk; const f32x2_t wv = *(const f32x2_t*)(wp + (size_t)kk * 6144);
; #pragma unroll
;             for (int s = 0; s < 5; ++s) { const float sv = sil[s * DM + k]; acc[s][0] += sv * wv.x; acc[s][1] += sv * wv.y; } }
	v_pk_fma_f32 v[6:7], v[68:69], v[22:23], v[6:7] op_sel_hi:[1,0,1]
	v_pk_fma_f32 v[8:9], v[68:69], v[30:31], v[8:9] op_sel_hi:[1,0,1]
	v_pk_fma_f32 v[10:11], v[68:69], v[38:39], v[10:11] op_sel_hi:[1,0,1]
	v_pk_fma_f32 v[12:13], v[68:69], v[46:47], v[12:13] op_sel_hi:[1,0,1]
	v_pk_fma_f32 v[4:5], v[68:69], v[54:55], v[4:5] op_sel_hi:[1,0,1]
	s_waitcnt vmcnt(8)
	v_pk_fma_f32 v[6:7], v[70:71], v[82:83], v[6:7] op_sel_hi:[1,0,1]
	v_pk_fma_f32 v[8:9], v[70:71], v[84:85], v[8:9] op_sel_hi:[1,0,1]
	v_pk_fma_f32 v[10:11], v[70:71], v[86:87], v[10:11] op_sel_hi:[1,0,1]
	v_pk_fma_f32 v[12:13], v[70:71], v[88:89], v[12:13] op_sel_hi:[1,0,1]
	v_pk_fma_f32 v[4:5], v[70:71], v[90:91], v[4:5] op_sel_hi:[1,0,1]
	v_lshl_add_u64 v[108:109], v[0:1], 0, s[6:7]
	s_add_u32 s6, s6, 0x30000
	s_addc_u32 s7, s7, 0
	global_load_dwordx2 v[56:57], v[108:109], off
	v_lshl_add_u64 v[110:111], v[108:109], 0, s[20:21]
	global_load_dwordx2 v[58:59], v[110:111], off
	v_lshl_add_u64 v[112:113], v[110:111], 0, s[20:21]
	global_load_dwordx2 v[60:61], v[112:113], off
	v_lshl_add_u64 v[114:115], v[112:113], 0, s[20:21]
	global_load_dwordx2 v[62:63], v[114:115], off
	v_lshl_add_u64 v[116:117], v[114:115], 0, s[20:21]
	global_load_dwordx2 v[64:65], v[116:117], off
	v_lshl_add_u64 v[118:119], v[116:117], 0, s[20:21]
	global_load_dwordx2 v[66:67], v[118:119], off
	v_lshl_add_u64 v[120:121], v[118:119], 0, s[20:21]
	global_load_dwordx2 v[68:69], v[120:121], off
	v_lshl_add_u64 v[122:123], v[120:121], 0, s[20:21]
	global_load_dwordx2 v[70:71], v[122:123], off
	v_mov_b32_e32 v52, s9
	s_add_i32 s9, s9, 32
	ds_read_b128 v[16:19], v52
	ds_read_b128 v[20:23], v52 offset:16
	ds_read_b128 v[24:27], v52 offset:4096
	ds_read_b128 v[28:31], v52 offset:4112
	ds_read_b128 v[32:35], v52 offset:8192
	ds_read_b128 v[36:39], v52 offset:8208
	ds_read_b128 v[40:43], v52 offset:12288
	ds_read_b128 v[44:47], v52 offset:12304
	ds_read_b128 v[48:51], v52 offset:16384
	ds_read_b128 v[52:55], v52 offset:16400
	s_waitcnt lgkmcnt(0)
	v_mov_b32_e32 v72, v19
	v_mov_b32_e32 v74, v27
	v_mov_b32_e32 v76, v35
	v_mov_b32_e32 v78, v43
	v_mov_b32_e32 v80, v51
	v_mov_b32_e32 v82, v23
	v_mov_b32_e32 v84, v31
	v_mov_b32_e32 v86, v39
	v_mov_b32_e32 v88, v47
	v_mov_b32_e32 v90, v55
	s_waitcnt vmcnt(15)
	v_pk_fma_f32 v[6:7], v[92:93], v[16:17], v[6:7] op_sel_hi:[1,0,1]
	v_pk_fma_f32 v[8:9], v[92:93], v[24:25], v[8:9] op_sel_hi:[1,0,1]
	v_pk_fma_f32 v[10:11], v[92:93], v[32:33], v[10:11] op_sel_hi:[1,0,1]
	v_pk_fma_f32 v[12:13], v[92:93], v[40:41], v[12:13] op_sel_hi:[1,0,1]
	v_pk_fma_f32 v[4:5], v[92:93], v[48:49], v[4:5] op_sel_hi:[1,0,1]
	s_waitcnt vmcnt(14)
	v_pk_fma_f32 v[6:7], v[94:95], v[16:17], v[6:7] op_sel:[0,1,0]
	v_pk_fma_f32 v[8:9], v[94:95], v[24:25], v[8:9] op_sel:[0,1,0]
	v_pk_fma_f32 v[10:11], v[94:95], v[32:33], v[10:11] op_sel:[0,1,0]
	v_pk_fma_f32 v[12:13], v[94:95], v[40:41], v[12:13] op_sel:[0,1,0]
	v_pk_fma_f32 v[4:5], v[94:95], v[48:49], v[4:5] op_sel:[0,1,0]
	s_waitcnt vmcnt(13)
	v_pk_fma_f32 v[6:7], v[96:97], v[18:19], v[6:7] op_sel_hi:[1,0,1]
	v_pk_fma_f32 v[8:9], v[96:97], v[26:27], v[8:9] op_sel_hi:[1,0,1]
	v_pk_fma_f32 v[10:11], v[96:97], v[34:35], v[10:11] op_sel_hi:[1,0,1]
	v_pk_fma_f32 v[12:13], v[96:97], v[42:43], v[12:13] op_sel_hi:[1,0,1]
	v_pk_fma_f32 v[4:5], v[96:97], v[50:51], v[4:5] op_sel_hi:[1,0,1]
	s_waitcnt vmcnt(12)
	v_pk_fma_f32 v[6:7], v[98:99], v[72:73], v[6:7] op_sel_hi:[1,0,1]
	v_pk_fma_f32 v[8:9], v[98:99], v[74:75], v[8:9] op_sel_hi:[1,0,1]
	v_pk_fma_f32 v[10:11], v[98:99], v[76:77], v[10:11] op_sel_hi:[1,0,1]
	v_pk_fma_f32 v[12:13], v[98:99], v[78:79], v[12:13] op_sel_hi:[1,0,1]
	v_pk_fma_f32 v[4:5], v[98:99], v[80:81], v[4:5] op_sel_hi:[1,0,1]
	s_waitcnt vmcnt(11)
	v_pk_fma_f32 v[6:7], v[100:101], v[20:21], v[6:7] op_sel_hi:[1,0,1]
	v_pk_fma_f32 v[8:9], v[100:101], v[28:29], v[8:9] op_sel_hi:[1,0,1]
	v_pk_fma_f32 v[10:11], v[100:101], v[36:37], v[10:11] op_sel_hi:[1,0,1]
	v_pk_fma_f32 v[12:13], v[100:101], v[44:45], v[12:13] op_sel_hi:[1,0,1]
	v_pk_fma_f32 v[4:5], v[100:101], v[52:53], v[4:5] op_sel_hi:[1,0,1]
	s_waitcnt vmcnt(10)
	v_pk_fma_f32 v[6:7], v[102:103], v[20:21], v[6:7] op_sel:[0,1,0]
	v_pk_fma_f32 v[8:9], v[102:103], v[28:29], v[8:9] op_sel:[0,1,0]
	v_pk_fma_f32 v[10:11], v[102:103], v[36:37], v[10:11] op_sel:[0,1,0]
	v_pk_fma_f32 v[12:13], v[102:103], v[44:45], v[12:13] op_sel:[0,1,0]
	v_pk_fma_f32 v[4:5], v[102:103], v[52:53], v[4:5] op_sel:[0,1,0]
	s_waitcnt vmcnt(9)
	v_pk_fma_f32 v[6:7], v[104:105], v[22:23], v[6:7] op_sel_hi:[1,0,1]
	v_pk_fma_f32 v[8:9], v[104:105], v[30:31], v[8:9] op_sel_hi:[1,0,1]
	v_pk_fma_f32 v[10:11], v[104:105], v[38:39], v[10:11] op_sel_hi:[1,0,1]
	v_pk_fma_f32 v[12:13], v[104:105], v[46:47], v[12:13] op_sel_hi:[1,0,1]
	v_pk_fma_f32 v[4:5], v[104:105], v[54:55], v[4:5] op_sel_hi:[1,0,1]
	s_waitcnt vmcnt(8)
	v_pk_fma_f32 v[6:7], v[106:107], v[82:83], v[6:7] op_sel_hi:[1,0,1]
	v_pk_fma_f32 v[8:9], v[106:107], v[84:85], v[8:9] op_sel_hi:[1,0,1]
	v_pk_fma_f32 v[10:11], v[106:107], v[86:87], v[10:11] op_sel_hi:[1,0,1]
	v_pk_fma_f32 v[12:13], v[106:107], v[88:89], v[12:13] op_sel_hi:[1,0,1]
	v_pk_fma_f32 v[4:5], v[106:107], v[90:91], v[4:5] op_sel_hi:[1,0,1]
	v_lshl_add_u64 v[108:109], v[0:1], 0, s[6:7]
	s_add_u32 s6, s6, 0x30000
	s_addc_u32 s7, s7, 0
	global_load_dwordx2 v[92:93], v[108:109], off
	v_lshl_add_u64 v[110:111], v[108:109], 0, s[20:21]
	global_load_dwordx2 v[94:95], v[110:111], off
	v_lshl_add_u64 v[112:113], v[110:111], 0, s[20:21]
	global_load_dwordx2 v[96:97], v[112:113], off
	v_lshl_add_u64 v[114:115], v[112:113], 0, s[20:21]
	global_load_dwordx2 v[98:99], v[114:115], off
	v_lshl_add_u64 v[116:117], v[114:115], 0, s[20:21]
	global_load_dwordx2 v[100:101], v[116:117], off
	v_lshl_add_u64 v[118:119], v[116:117], 0, s[20:21]
	global_load_dwordx2 v[102:103], v[118:119], off
	v_lshl_add_u64 v[120:121], v[118:119], 0, s[20:21]
	global_load_dwordx2 v[104:105], v[120:121], off
	v_lshl_add_u64 v[122:123], v[120:121], 0, s[20:21]
	global_load_dwordx2 v[106:107], v[122:123], off
	v_mov_b32_e32 v52, s9
	s_add_i32 s9, s9, 32
	ds_read_b128 v[16:19], v52
	ds_read_b128 v[20:23], v52 offset:16
	ds_read_b128 v[24:27], v52 offset:4096
	ds_read_b128 v[28:31], v52 offset:4112
	ds_read_b128 v[32:35], v52 offset:8192
	ds_read_b128 v[36:39], v52 offset:8208
	ds_read_b128 v[40:43], v52 offset:12288
	ds_read_b128 v[44:47], v52 offset:12304
	ds_read_b128 v[48:51], v52 offset:16384
	ds_read_b128 v[52:55], v52 offset:16400
	s_waitcnt lgkmcnt(0)
; __device__ __forceinline__ void prologue_phase(const Args& a, LAS unsigned char* lds) {
;     ...
;         const float* wp = a.ada_w + ((size_t)l * DM + 128 * w) * 6144 + j;
; #pragma unroll 8
;         for (int kk = 0; kk < 128; ++kk) { const int k = 128 * w + kk; const f32x2_t wv = *(const f32x2_t*)(wp + (size_t)kk * 6144);
; #pragma unroll
;             for (int s = 0; s < 5; ++s) { const float sv = sil[s * DM + k]; acc[s][0] += sv * wv.x; acc[s][1] += sv * wv.y; } }
	v_mov_b32_e32 v72, v19
	v_mov_b32_e32 v74, v27
	v_mov_b32_e32 v76, v35
	v_mov_b32_e32 v78, v43
	v_mov_b32_e32 v80, v51
	v_mov_b32_e32 v82, v23
	v_mov_b32_e32 v84, v31
	v_mov_b32_e32 v86, v39
	v_mov_b32_e32 v88, v47
	v_mov_b32_e32 v90, v55
	s_waitcnt vmcnt(15)
	v_pk_fma_f32 v[6:7], v[56:57], v[16:17], v[6:7] op_sel_hi:[1,0,1]
	v_pk_fma_f32 v[8:9], v[56:57], v[24:25], v[8:9] op_sel_hi:[1,0,1]
	v_pk_fma_f32 v[10:11], v[56:57], v[32:33], v[10:11] op_sel_hi:[1,0,1]
	v_pk_fma_f32 v[12:13], v[56:57], v[40:41], v[12:13] op_sel_hi:[1,0,1]
	v_pk_fma_f32 v[4:5], v[56:57], v[48:49], v[4:5] op_sel_hi:[1,0,1]
	s_waitcnt vmcnt(14)
	v_pk_fma_f32 v[6:7], v[58:59], v[16:17], v[6:7] op_sel:[0,1,0]
	v_pk_fma_f32 v[8:9], v[58:59], v[24:25], v[8:9] op_sel:[0,1,0]
	v_pk_fma_f32 v[10:11], v[58:59], v[32:33], v[10:11] op_sel:[0,1,0]
	v_pk_fma_f32 v[12:13], v[58:59], v[40:41], v[12:13] op_sel:[0,1,0]
	v_pk_fma_f32 v[4:5], v[58:59], v[48:49], v[4:5] op_sel:[0,1,0]
	s_waitcnt vmcnt(13)
	v_pk_fma_f32 v[6:7], v[60:61], v[18:19], v[6:7] op_sel_hi:[1,0,1]
	v_pk_fma_f32 v[8:9], v[60:61], v[26:27], v[8:9] op_sel_hi:[1,0,1]
	v_pk_fma_f32 v[10:11], v[60:61], v[34:35], v[10:11] op_sel_hi:[1,0,1]
	v_pk_fma_f32 v[12:13], v[60:61], v[42:43], v[12:13] op_sel_hi:[1,0,1]
	v_pk_fma_f32 v[4:5], v[60:61], v[50:51], v[4:5] op_sel_hi:[1,0,1]
	s_waitcnt vmcnt(12)
	v_pk_fma_f32 v[6:7], v[62:63], v[72:73], v[6:7] op_sel_hi:[1,0,1]
	v_pk_fma_f32 v[8:9], v[62:63], v[74:75], v[8:9] op_sel_hi:[1,0,1]
	v_pk_fma_f32 v[10:11], v[62:63], v[76:77], v[10:11] op_sel_hi:[1,0,1]
	v_pk_fma_f32 v[12:13], v[62:63], v[78:79], v[12:13] op_sel_hi:[1,0,1]
	v_pk_fma_f32 v[4:5], v[62:63], v[80:81], v[4:5] op_sel_hi:[1,0,1]
	s_waitcnt vmcnt(11)
	v_pk_fma_f32 v[6:7], v[64:65], v[20:21], v[6:7] op_sel_hi:[1,0,1]
	v_pk_fma_f32 v[8:9], v[64:65], v[28:29], v[8:9] op_sel_hi:[1,0,1]
	v_pk_fma_f32 v[10:11], v[64:65], v[36:37], v[10:11] op_sel_hi:[1,0,1]
	v_pk_fma_f32 v[12:13], v[64:65], v[44:45], v[12:13] op_sel_hi:[1,0,1]
	v_pk_fma_f32 v[4:5], v[64:65], v[52:53], v[4:5] op_sel_hi:[1,0,1]
	s_waitcnt vmcnt(10)
	v_pk_fma_f32 v[6:7], v[66:67], v[20:21], v[6:7] op_sel:[0,1,0]
	v_pk_fma_f32 v[8:9], v[66:67], v[28:29], v[8:9] op_sel:[0,1,0]
	v_pk_fma_f32 v[10:11], v[66:67], v[36:37], v[10:11] op_sel:[0,1,0]
	v_pk_fma_f32 v[12:13], v[66:67], v[44:45], v[12:13] op_sel:[0,1,0]
	v_pk_fma_f32 v[4:5], v[66:67], v[52:53], v[4:5] op_sel:[0,1,0]
	s_waitcnt vmcnt(9)
	v_pk_fma_f32 v[6:7], v[68:69], v[22:23], v[6:7] op_sel_hi:[1,0,1]
	v_pk_fma_f32 v[8:9], v[68:69], v[30:31], v[8:9] op_sel_hi:[1,0,1]
	v_pk_fma_f32 v[10:11], v[68:69], v[38:39], v[10:11] op_sel_hi:[1,0,1]
	v_pk_fma_f32 v[12:13], v[68:69], v[46:47], v[12:13] op_sel_hi:[1,0,1]
	v_pk_fma_f32 v[4:5], v[68:69], v[54:55], v[4:5] op_sel_hi:[1,0,1]
	s_waitcnt vmcnt(8)
	v_pk_fma_f32 v[6:7], v[70:71], v[82:83], v[6:7] op_sel_hi:[1,0,1]
	v_pk_fma_f32 v[8:9], v[70:71], v[84:85], v[8:9] op_sel_hi:[1,0,1]
	v_pk_fma_f32 v[10:11], v[70:71], v[86:87], v[10:11] op_sel_hi:[1,0,1]
	v_pk_fma_f32 v[12:13], v[70:71], v[88:89], v[12:13] op_sel_hi:[1,0,1]
	v_pk_fma_f32 v[4:5], v[70:71], v[90:91], v[4:5] op_sel_hi:[1,0,1]
	v_lshl_add_u64 v[108:109], v[0:1], 0, s[6:7]
	s_add_u32 s6, s6, 0x30000
	s_addc_u32 s7, s7, 0
	global_load_dwordx2 v[56:57], v[108:109], off
	v_lshl_add_u64 v[110:111], v[108:109], 0, s[20:21]
	global_load_dwordx2 v[58:59], v[110:111], off
	v_lshl_add_u64 v[112:113], v[110:111], 0, s[20:21]
	global_load_dwordx2 v[60:61], v[112:113], off
	v_lshl_add_u64 v[114:115], v[112:113], 0, s[20:21]
	global_load_dwordx2 v[62:63], v[114:115], off
	v_lshl_add_u64 v[116:117], v[114:115], 0, s[20:21]
	global_load_dwordx2 v[64:65], v[116:117], off
	v_lshl_add_u64 v[118:119], v[116:117], 0, s[20:21]
	global_load_dwordx2 v[66:67], v[118:119], off
	v_lshl_add_u64 v[120:121], v[118:119], 0, s[20:21]
	global_load_dwordx2 v[68:69], v[120:121], off
	v_lshl_add_u64 v[122:123], v[120:121], 0, s[20:21]
	global_load_dwordx2 v[70:71], v[122:123], off
	v_mov_b32_e32 v52, s9
	s_add_i32 s9, s9, 32
	ds_read_b128 v[16:19], v52
	ds_read_b128 v[20:23], v52 offset:16
	ds_read_b128 v[24:27], v52 offset:4096
	ds_read_b128 v[28:31], v52 offset:4112
	ds_read_b128 v[32:35], v52 offset:8192
	ds_read_b128 v[36:39], v52 offset:8208
	ds_read_b128 v[40:43], v52 offset:12288
	ds_read_b128 v[44:47], v52 offset:12304
	ds_read_b128 v[48:51], v52 offset:16384
	ds_read_b128 v[52:55], v52 offset:16400
	s_waitcnt lgkmcnt(0)
	v_mov_b32_e32 v72, v19
	v_mov_b32_e32 v74, v27
	v_mov_b32_e32 v76, v35
	v_mov_b32_e32 v78, v43
	v_mov_b32_e32 v80, v51
	v_mov_b32_e32 v82, v23
	v_mov_b32_e32 v84, v31
	v_mov_b32_e32 v86, v39
	v_mov_b32_e32 v88, v47
	v_mov_b32_e32 v90, v55
	s_waitcnt vmcnt(15)
	v_pk_fma_f32 v[6:7], v[92:93], v[16:17], v[6:7] op_sel_hi:[1,0,1]
	v_pk_fma_f32 v[8:9], v[92:93], v[24:25], v[8:9] op_sel_hi:[1,0,1]
	v_pk_fma_f32 v[10:11], v[92:93], v[32:33], v[10:11] op_sel_hi:[1,0,1]
	v_pk_fma_f32 v[12:13], v[92:93], v[40:41], v[12:13] op_sel_hi:[1,0,1]
	v_pk_fma_f32 v[4:5], v[92:93], v[48:49], v[4:5] op_sel_hi:[1,0,1]
	s_waitcnt vmcnt(14)
	v_pk_fma_f32 v[6:7], v[94:95], v[16:17], v[6:7] op_sel:[0,1,0]
	v_pk_fma_f32 v[8:9], v[94:95], v[24:25], v[8:9] op_sel:[0,1,0]
	v_pk_fma_f32 v[10:11], v[94:95], v[32:33], v[10:11] op_sel:[0,1,0]
	v_pk_fma_f32 v[12:13], v[94:95], v[40:41], v[12:13] op_sel:[0,1,0]
	v_pk_fma_f32 v[4:5], v[94:95], v[48:49], v[4:5] op_sel:[0,1,0]
	s_waitcnt vmcnt(13)
	v_pk_fma_f32 v[6:7], v[96:97], v[18:19], v[6:7] op_sel_hi:[1,0,1]
	v_pk_fma_f32 v[8:9], v[96:97], v[26:27], v[8:9] op_sel_hi:[1,0,1]
	v_pk_fma_f32 v[10:11], v[96:97], v[34:35], v[10:11] op_sel_hi:[1,0,1]
	v_pk_fma_f32 v[12:13], v[96:97], v[42:43], v[12:13] op_sel_hi:[1,0,1]
	v_pk_fma_f32 v[4:5], v[96:97], v[50:51], v[4:5] op_sel_hi:[1,0,1]
	s_waitcnt vmcnt(12)
; __device__ __forceinline__ void prologue_phase(const Args& a, LAS unsigned char* lds) {
;     ...
;         const float* wp = a.ada_w + ((size_t)l * DM + 128 * w) * 6144 + j;
; #pragma unroll 8
;         for (int kk = 0; kk < 128; ++kk) { const int k = 128 * w + kk; const f32x2_t wv = *(const f32x2_t*)(wp + (size_t)kk * 6144);
; #pragma unroll
;             for (int s = 0; s < 5; ++s) { const float sv = sil[s * DM + k]; acc[s][0] += sv * wv.x; acc[s][1] += sv * wv.y; } }
	v_pk_fma_f32 v[6:7], v[98:99], v[72:73], v[6:7] op_sel_hi:[1,0,1]
	v_pk_fma_f32 v[8:9], v[98:99], v[74:75], v[8:9] op_sel_hi:[1,0,1]
	v_pk_fma_f32 v[10:11], v[98:99], v[76:77], v[10:11] op_sel_hi:[1,0,1]
	v_pk_fma_f32 v[12:13], v[98:99], v[78:79], v[12:13] op_sel_hi:[1,0,1]
	v_pk_fma_f32 v[4:5], v[98:99], v[80:81], v[4:5] op_sel_hi:[1,0,1]
	s_waitcnt vmcnt(11)
	v_pk_fma_f32 v[6:7], v[100:101], v[20:21], v[6:7] op_sel_hi:[1,0,1]
	v_pk_fma_f32 v[8:9], v[100:101], v[28:29], v[8:9] op_sel_hi:[1,0,1]
	v_pk_fma_f32 v[10:11], v[100:101], v[36:37], v[10:11] op_sel_hi:[1,0,1]
	v_pk_fma_f32 v[12:13], v[100:101], v[44:45], v[12:13] op_sel_hi:[1,0,1]
	v_pk_fma_f32 v[4:5], v[100:101], v[52:53], v[4:5] op_sel_hi:[1,0,1]
	s_waitcnt vmcnt(10)
	v_pk_fma_f32 v[6:7], v[102:103], v[20:21], v[6:7] op_sel:[0,1,0]
	v_pk_fma_f32 v[8:9], v[102:103], v[28:29], v[8:9] op_sel:[0,1,0]
	v_pk_fma_f32 v[10:11], v[102:103], v[36:37], v[10:11] op_sel:[0,1,0]
	v_pk_fma_f32 v[12:13], v[102:103], v[44:45], v[12:13] op_sel:[0,1,0]
	v_pk_fma_f32 v[4:5], v[102:103], v[52:53], v[4:5] op_sel:[0,1,0]
	s_waitcnt vmcnt(9)
	v_pk_fma_f32 v[6:7], v[104:105], v[22:23], v[6:7] op_sel_hi:[1,0,1]
	v_pk_fma_f32 v[8:9], v[104:105], v[30:31], v[8:9] op_sel_hi:[1,0,1]
	v_pk_fma_f32 v[10:11], v[104:105], v[38:39], v[10:11] op_sel_hi:[1,0,1]
	v_pk_fma_f32 v[12:13], v[104:105], v[46:47], v[12:13] op_sel_hi:[1,0,1]
	v_pk_fma_f32 v[4:5], v[104:105], v[54:55], v[4:5] op_sel_hi:[1,0,1]
	s_waitcnt vmcnt(8)
	v_pk_fma_f32 v[6:7], v[106:107], v[82:83], v[6:7] op_sel_hi:[1,0,1]
	v_pk_fma_f32 v[8:9], v[106:107], v[84:85], v[8:9] op_sel_hi:[1,0,1]
	v_pk_fma_f32 v[10:11], v[106:107], v[86:87], v[10:11] op_sel_hi:[1,0,1]
	v_pk_fma_f32 v[12:13], v[106:107], v[88:89], v[12:13] op_sel_hi:[1,0,1]
	v_pk_fma_f32 v[4:5], v[106:107], v[90:91], v[4:5] op_sel_hi:[1,0,1]
	v_lshl_add_u64 v[108:109], v[0:1], 0, s[6:7]
	s_add_u32 s6, s6, 0x30000
	s_addc_u32 s7, s7, 0
	global_load_dwordx2 v[92:93], v[108:109], off
	v_lshl_add_u64 v[110:111], v[108:109], 0, s[20:21]
	global_load_dwordx2 v[94:95], v[110:111], off
	v_lshl_add_u64 v[112:113], v[110:111], 0, s[20:21]
	global_load_dwordx2 v[96:97], v[112:113], off
	v_lshl_add_u64 v[114:115], v[112:113], 0, s[20:21]
	global_load_dwordx2 v[98:99], v[114:115], off
	v_lshl_add_u64 v[116:117], v[114:115], 0, s[20:21]
	global_load_dwordx2 v[100:101], v[116:117], off
	v_lshl_add_u64 v[118:119], v[116:117], 0, s[20:21]
	global_load_dwordx2 v[102:103], v[118:119], off
	v_lshl_add_u64 v[120:121], v[118:119], 0, s[20:21]
	global_load_dwordx2 v[104:105], v[120:121], off
	v_lshl_add_u64 v[122:123], v[120:121], 0, s[20:21]
	global_load_dwordx2 v[106:107], v[122:123], off
	v_mov_b32_e32 v52, s9
	s_add_i32 s9, s9, 32
	ds_read_b128 v[16:19], v52
	ds_read_b128 v[20:23], v52 offset:16
	ds_read_b128 v[24:27], v52 offset:4096
	ds_read_b128 v[28:31], v52 offset:4112
	ds_read_b128 v[32:35], v52 offset:8192
	ds_read_b128 v[36:39], v52 offset:8208
	ds_read_b128 v[40:43], v52 offset:12288
	ds_read_b128 v[44:47], v52 offset:12304
	ds_read_b128 v[48:51], v52 offset:16384
	ds_read_b128 v[52:55], v52 offset:16400
	s_waitcnt lgkmcnt(0)
	v_mov_b32_e32 v72, v19
	v_mov_b32_e32 v74, v27
	v_mov_b32_e32 v76, v35
	v_mov_b32_e32 v78, v43
	v_mov_b32_e32 v80, v51
	v_mov_b32_e32 v82, v23
	v_mov_b32_e32 v84, v31
	v_mov_b32_e32 v86, v39
	v_mov_b32_e32 v88, v47
	v_mov_b32_e32 v90, v55
	s_waitcnt vmcnt(15)
	v_pk_fma_f32 v[6:7], v[56:57], v[16:17], v[6:7] op_sel_hi:[1,0,1]
	v_pk_fma_f32 v[8:9], v[56:57], v[24:25], v[8:9] op_sel_hi:[1,0,1]
	v_pk_fma_f32 v[10:11], v[56:57], v[32:33], v[10:11] op_sel_hi:[1,0,1]
	v_pk_fma_f32 v[12:13], v[56:57], v[40:41], v[12:13] op_sel_hi:[1,0,1]
	v_pk_fma_f32 v[4:5], v[56:57], v[48:49], v[4:5] op_sel_hi:[1,0,1]
	s_waitcnt vmcnt(14)
	v_pk_fma_f32 v[6:7], v[58:59], v[16:17], v[6:7] op_sel:[0,1,0]
	v_pk_fma_f32 v[8:9], v[58:59], v[24:25], v[8:9] op_sel:[0,1,0]
	v_pk_fma_f32 v[10:11], v[58:59], v[32:33], v[10:11] op_sel:[0,1,0]
	v_pk_fma_f32 v[12:13], v[58:59], v[40:41], v[12:13] op_sel:[0,1,0]
	v_pk_fma_f32 v[4:5], v[58:59], v[48:49], v[4:5] op_sel:[0,1,0]
	s_waitcnt vmcnt(13)
	v_pk_fma_f32 v[6:7], v[60:61], v[18:19], v[6:7] op_sel_hi:[1,0,1]
	v_pk_fma_f32 v[8:9], v[60:61], v[26:27], v[8:9] op_sel_hi:[1,0,1]
	v_pk_fma_f32 v[10:11], v[60:61], v[34:35], v[10:11] op_sel_hi:[1,0,1]
	v_pk_fma_f32 v[12:13], v[60:61], v[42:43], v[12:13] op_sel_hi:[1,0,1]
	v_pk_fma_f32 v[4:5], v[60:61], v[50:51], v[4:5] op_sel_hi:[1,0,1]
	s_waitcnt vmcnt(12)
	v_pk_fma_f32 v[6:7], v[62:63], v[72:73], v[6:7] op_sel_hi:[1,0,1]
	v_pk_fma_f32 v[8:9], v[62:63], v[74:75], v[8:9] op_sel_hi:[1,0,1]
	v_pk_fma_f32 v[10:11], v[62:63], v[76:77], v[10:11] op_sel_hi:[1,0,1]
	v_pk_fma_f32 v[12:13], v[62:63], v[78:79], v[12:13] op_sel_hi:[1,0,1]
	v_pk_fma_f32 v[4:5], v[62:63], v[80:81], v[4:5] op_sel_hi:[1,0,1]
	s_waitcnt vmcnt(11)
	v_pk_fma_f32 v[6:7], v[64:65], v[20:21], v[6:7] op_sel_hi:[1,0,1]
	v_pk_fma_f32 v[8:9], v[64:65], v[28:29], v[8:9] op_sel_hi:[1,0,1]
	v_pk_fma_f32 v[10:11], v[64:65], v[36:37], v[10:11] op_sel_hi:[1,0,1]
	v_pk_fma_f32 v[12:13], v[64:65], v[44:45], v[12:13] op_sel_hi:[1,0,1]
	v_pk_fma_f32 v[4:5], v[64:65], v[52:53], v[4:5] op_sel_hi:[1,0,1]
	s_waitcnt vmcnt(10)
	v_pk_fma_f32 v[6:7], v[66:67], v[20:21], v[6:7] op_sel:[0,1,0]
	v_pk_fma_f32 v[8:9], v[66:67], v[28:29], v[8:9] op_sel:[0,1,0]
	v_pk_fma_f32 v[10:11], v[66:67], v[36:37], v[10:11] op_sel:[0,1,0]
	v_pk_fma_f32 v[12:13], v[66:67], v[44:45], v[12:13] op_sel:[0,1,0]
	v_pk_fma_f32 v[4:5], v[66:67], v[52:53], v[4:5] op_sel:[0,1,0]
	s_waitcnt vmcnt(9)
; __device__ __forceinline__ void prologue_phase(const Args& a, LAS unsigned char* lds) {
;     ...
;         const float* wp = a.ada_w + ((size_t)l * DM + 128 * w) * 6144 + j;
; #pragma unroll 8
;         for (int kk = 0; kk < 128; ++kk) { const int k = 128 * w + kk; const f32x2_t wv = *(const f32x2_t*)(wp + (size_t)kk * 6144);
; #pragma unroll
;             for (int s = 0; s < 5; ++s) { const float sv = sil[s * DM + k]; acc[s][0] += sv * wv.x; acc[s][1] += sv * wv.y; } }
	v_pk_fma_f32 v[6:7], v[68:69], v[22:23], v[6:7] op_sel_hi:[1,0,1]
	v_pk_fma_f32 v[8:9], v[68:69], v[30:31], v[8:9] op_sel_hi:[1,0,1]
	v_pk_fma_f32 v[10:11], v[68:69], v[38:39], v[10:11] op_sel_hi:[1,0,1]
	v_pk_fma_f32 v[12:13], v[68:69], v[46:47], v[12:13] op_sel_hi:[1,0,1]
	v_pk_fma_f32 v[4:5], v[68:69], v[54:55], v[4:5] op_sel_hi:[1,0,1]
	s_waitcnt vmcnt(8)
	v_pk_fma_f32 v[6:7], v[70:71], v[82:83], v[6:7] op_sel_hi:[1,0,1]
	v_pk_fma_f32 v[8:9], v[70:71], v[84:85], v[8:9] op_sel_hi:[1,0,1]
	v_pk_fma_f32 v[10:11], v[70:71], v[86:87], v[10:11] op_sel_hi:[1,0,1]
	v_pk_fma_f32 v[12:13], v[70:71], v[88:89], v[12:13] op_sel_hi:[1,0,1]
	v_pk_fma_f32 v[4:5], v[70:71], v[90:91], v[4:5] op_sel_hi:[1,0,1]
	v_lshl_add_u64 v[108:109], v[0:1], 0, s[6:7]
	s_add_u32 s6, s6, 0x30000
	s_addc_u32 s7, s7, 0
	global_load_dwordx2 v[56:57], v[108:109], off
	v_lshl_add_u64 v[110:111], v[108:109], 0, s[20:21]
	global_load_dwordx2 v[58:59], v[110:111], off
	v_lshl_add_u64 v[112:113], v[110:111], 0, s[20:21]
	global_load_dwordx2 v[60:61], v[112:113], off
	v_lshl_add_u64 v[114:115], v[112:113], 0, s[20:21]
	global_load_dwordx2 v[62:63], v[114:115], off
	v_lshl_add_u64 v[116:117], v[114:115], 0, s[20:21]
	global_load_dwordx2 v[64:65], v[116:117], off
	v_lshl_add_u64 v[118:119], v[116:117], 0, s[20:21]
	global_load_dwordx2 v[66:67], v[118:119], off
	v_lshl_add_u64 v[120:121], v[118:119], 0, s[20:21]
	global_load_dwordx2 v[68:69], v[120:121], off
	v_lshl_add_u64 v[122:123], v[120:121], 0, s[20:21]
	global_load_dwordx2 v[70:71], v[122:123], off
	v_mov_b32_e32 v52, s9
	s_add_i32 s9, s9, 32
	ds_read_b128 v[16:19], v52
	ds_read_b128 v[20:23], v52 offset:16
	ds_read_b128 v[24:27], v52 offset:4096
	ds_read_b128 v[28:31], v52 offset:4112
	ds_read_b128 v[32:35], v52 offset:8192
	ds_read_b128 v[36:39], v52 offset:8208
	ds_read_b128 v[40:43], v52 offset:12288
	ds_read_b128 v[44:47], v52 offset:12304
	ds_read_b128 v[48:51], v52 offset:16384
	ds_read_b128 v[52:55], v52 offset:16400
	s_waitcnt lgkmcnt(0)
	v_mov_b32_e32 v72, v19
	v_mov_b32_e32 v74, v27
	v_mov_b32_e32 v76, v35
	v_mov_b32_e32 v78, v43
	v_mov_b32_e32 v80, v51
	v_mov_b32_e32 v82, v23
	v_mov_b32_e32 v84, v31
	v_mov_b32_e32 v86, v39
	v_mov_b32_e32 v88, v47
	v_mov_b32_e32 v90, v55
	s_waitcnt vmcnt(15)
	v_pk_fma_f32 v[6:7], v[92:93], v[16:17], v[6:7] op_sel_hi:[1,0,1]
	v_pk_fma_f32 v[8:9], v[92:93], v[24:25], v[8:9] op_sel_hi:[1,0,1]
	v_pk_fma_f32 v[10:11], v[92:93], v[32:33], v[10:11] op_sel_hi:[1,0,1]
	v_pk_fma_f32 v[12:13], v[92:93], v[40:41], v[12:13] op_sel_hi:[1,0,1]
	v_pk_fma_f32 v[4:5], v[92:93], v[48:49], v[4:5] op_sel_hi:[1,0,1]
	s_waitcnt vmcnt(14)
	v_pk_fma_f32 v[6:7], v[94:95], v[16:17], v[6:7] op_sel:[0,1,0]
	v_pk_fma_f32 v[8:9], v[94:95], v[24:25], v[8:9] op_sel:[0,1,0]
	v_pk_fma_f32 v[10:11], v[94:95], v[32:33], v[10:11] op_sel:[0,1,0]
	v_pk_fma_f32 v[12:13], v[94:95], v[40:41], v[12:13] op_sel:[0,1,0]
	v_pk_fma_f32 v[4:5], v[94:95], v[48:49], v[4:5] op_sel:[0,1,0]
	s_waitcnt vmcnt(13)
	v_pk_fma_f32 v[6:7], v[96:97], v[18:19], v[6:7] op_sel_hi:[1,0,1]
	v_pk_fma_f32 v[8:9], v[96:97], v[26:27], v[8:9] op_sel_hi:[1,0,1]
	v_pk_fma_f32 v[10:11], v[96:97], v[34:35], v[10:11] op_sel_hi:[1,0,1]
	v_pk_fma_f32 v[12:13], v[96:97], v[42:43], v[12:13] op_sel_hi:[1,0,1]
	v_pk_fma_f32 v[4:5], v[96:97], v[50:51], v[4:5] op_sel_hi:[1,0,1]
	s_waitcnt vmcnt(12)
	v_pk_fma_f32 v[6:7], v[98:99], v[72:73], v[6:7] op_sel_hi:[1,0,1]
	v_pk_fma_f32 v[8:9], v[98:99], v[74:75], v[8:9] op_sel_hi:[1,0,1]
	v_pk_fma_f32 v[10:11], v[98:99], v[76:77], v[10:11] op_sel_hi:[1,0,1]
	v_pk_fma_f32 v[12:13], v[98:99], v[78:79], v[12:13] op_sel_hi:[1,0,1]
	v_pk_fma_f32 v[4:5], v[98:99], v[80:81], v[4:5] op_sel_hi:[1,0,1]
	s_waitcnt vmcnt(11)
	v_pk_fma_f32 v[6:7], v[100:101], v[20:21], v[6:7] op_sel_hi:[1,0,1]
	v_pk_fma_f32 v[8:9], v[100:101], v[28:29], v[8:9] op_sel_hi:[1,0,1]
	v_pk_fma_f32 v[10:11], v[100:101], v[36:37], v[10:11] op_sel_hi:[1,0,1]
	v_pk_fma_f32 v[12:13], v[100:101], v[44:45], v[12:13] op_sel_hi:[1,0,1]
	v_pk_fma_f32 v[4:5], v[100:101], v[52:53], v[4:5] op_sel_hi:[1,0,1]
	s_waitcnt vmcnt(10)
	v_pk_fma_f32 v[6:7], v[102:103], v[20:21], v[6:7] op_sel:[0,1,0]
	v_pk_fma_f32 v[8:9], v[102:103], v[28:29], v[8:9] op_sel:[0,1,0]
	v_pk_fma_f32 v[10:11], v[102:103], v[36:37], v[10:11] op_sel:[0,1,0]
	v_pk_fma_f32 v[12:13], v[102:103], v[44:45], v[12:13] op_sel:[0,1,0]
	v_pk_fma_f32 v[4:5], v[102:103], v[52:53], v[4:5] op_sel:[0,1,0]
	s_waitcnt vmcnt(9)
	v_pk_fma_f32 v[6:7], v[104:105], v[22:23], v[6:7] op_sel_hi:[1,0,1]
	v_pk_fma_f32 v[8:9], v[104:105], v[30:31], v[8:9] op_sel_hi:[1,0,1]
	v_pk_fma_f32 v[10:11], v[104:105], v[38:39], v[10:11] op_sel_hi:[1,0,1]
	v_pk_fma_f32 v[12:13], v[104:105], v[46:47], v[12:13] op_sel_hi:[1,0,1]
	v_pk_fma_f32 v[4:5], v[104:105], v[54:55], v[4:5] op_sel_hi:[1,0,1]
	s_waitcnt vmcnt(8)
	v_pk_fma_f32 v[6:7], v[106:107], v[82:83], v[6:7] op_sel_hi:[1,0,1]
	v_pk_fma_f32 v[8:9], v[106:107], v[84:85], v[8:9] op_sel_hi:[1,0,1]
	v_pk_fma_f32 v[10:11], v[106:107], v[86:87], v[10:11] op_sel_hi:[1,0,1]
	v_pk_fma_f32 v[12:13], v[106:107], v[88:89], v[12:13] op_sel_hi:[1,0,1]
	v_pk_fma_f32 v[4:5], v[106:107], v[90:91], v[4:5] op_sel_hi:[1,0,1]
	v_lshl_add_u64 v[108:109], v[0:1], 0, s[6:7]
	s_add_u32 s6, s6, 0x30000
	s_addc_u32 s7, s7, 0
	global_load_dwordx2 v[92:93], v[108:109], off
	v_lshl_add_u64 v[110:111], v[108:109], 0, s[20:21]
	global_load_dwordx2 v[94:95], v[110:111], off
	v_lshl_add_u64 v[112:113], v[110:111], 0, s[20:21]
	global_load_dwordx2 v[96:97], v[112:113], off
	v_lshl_add_u64 v[114:115], v[112:113], 0, s[20:21]
	global_load_dwordx2 v[98:99], v[114:115], off
	v_lshl_add_u64 v[116:117], v[114:115], 0, s[20:21]
	global_load_dwordx2 v[100:101], v[116:117], off
	v_lshl_add_u64 v[118:119], v[116:117], 0, s[20:21]
	global_load_dwordx2 v[102:103], v[118:119], off
	v_lshl_add_u64 v[120:121], v[118:119], 0, s[20:21]
	global_load_dwordx2 v[104:105], v[120:121], off
	v_lshl_add_u64 v[122:123], v[120:121], 0, s[20:21]
	global_load_dwordx2 v[106:107], v[122:123], off
	v_mov_b32_e32 v52, s9
	s_add_i32 s9, s9, 32
	ds_read_b128 v[16:19], v52
	ds_read_b128 v[20:23], v52 offset:16
	ds_read_b128 v[24:27], v52 offset:4096
	ds_read_b128 v[28:31], v52 offset:4112
	ds_read_b128 v[32:35], v52 offset:8192
	ds_read_b128 v[36:39], v52 offset:8208
	ds_read_b128 v[40:43], v52 offset:12288
	ds_read_b128 v[44:47], v52 offset:12304
	ds_read_b128 v[48:51], v52 offset:16384
	ds_read_b128 v[52:55], v52 offset:16400
	s_waitcnt lgkmcnt(0)
; __device__ __forceinline__ void prologue_phase(const Args& a, LAS unsigned char* lds) {
;     ...
;         const float* wp = a.ada_w + ((size_t)l * DM + 128 * w) * 6144 + j;
; #pragma unroll 8
;         for (int kk = 0; kk < 128; ++kk) { const int k = 128 * w + kk; const f32x2_t wv = *(const f32x2_t*)(wp + (size_t)kk * 6144);
; #pragma unroll
;             for (int s = 0; s < 5; ++s) { const float sv = sil[s * DM + k]; acc[s][0] += sv * wv.x; acc[s][1] += sv * wv.y; } }
	v_mov_b32_e32 v72, v19
	v_mov_b32_e32 v74, v27
	v_mov_b32_e32 v76, v35
	v_mov_b32_e32 v78, v43
	v_mov_b32_e32 v80, v51
	v_mov_b32_e32 v82, v23
	v_mov_b32_e32 v84, v31
	v_mov_b32_e32 v86, v39
	v_mov_b32_e32 v88, v47
	v_mov_b32_e32 v90, v55
	s_waitcnt vmcnt(15)
	v_pk_fma_f32 v[6:7], v[56:57], v[16:17], v[6:7] op_sel_hi:[1,0,1]
	v_pk_fma_f32 v[8:9], v[56:57], v[24:25], v[8:9] op_sel_hi:[1,0,1]
	v_pk_fma_f32 v[10:11], v[56:57], v[32:33], v[10:11] op_sel_hi:[1,0,1]
	v_pk_fma_f32 v[12:13], v[56:57], v[40:41], v[12:13] op_sel_hi:[1,0,1]
	v_pk_fma_f32 v[4:5], v[56:57], v[48:49], v[4:5] op_sel_hi:[1,0,1]
	s_waitcnt vmcnt(14)
	v_pk_fma_f32 v[6:7], v[58:59], v[16:17], v[6:7] op_sel:[0,1,0]
	v_pk_fma_f32 v[8:9], v[58:59], v[24:25], v[8:9] op_sel:[0,1,0]
	v_pk_fma_f32 v[10:11], v[58:59], v[32:33], v[10:11] op_sel:[0,1,0]
	v_pk_fma_f32 v[12:13], v[58:59], v[40:41], v[12:13] op_sel:[0,1,0]
	v_pk_fma_f32 v[4:5], v[58:59], v[48:49], v[4:5] op_sel:[0,1,0]
	s_waitcnt vmcnt(13)
	v_pk_fma_f32 v[6:7], v[60:61], v[18:19], v[6:7] op_sel_hi:[1,0,1]
	v_pk_fma_f32 v[8:9], v[60:61], v[26:27], v[8:9] op_sel_hi:[1,0,1]
	v_pk_fma_f32 v[10:11], v[60:61], v[34:35], v[10:11] op_sel_hi:[1,0,1]
	v_pk_fma_f32 v[12:13], v[60:61], v[42:43], v[12:13] op_sel_hi:[1,0,1]
	v_pk_fma_f32 v[4:5], v[60:61], v[50:51], v[4:5] op_sel_hi:[1,0,1]
	s_waitcnt vmcnt(12)
	v_pk_fma_f32 v[6:7], v[62:63], v[72:73], v[6:7] op_sel_hi:[1,0,1]
	v_pk_fma_f32 v[8:9], v[62:63], v[74:75], v[8:9] op_sel_hi:[1,0,1]
	v_pk_fma_f32 v[10:11], v[62:63], v[76:77], v[10:11] op_sel_hi:[1,0,1]
	v_pk_fma_f32 v[12:13], v[62:63], v[78:79], v[12:13] op_sel_hi:[1,0,1]
	v_pk_fma_f32 v[4:5], v[62:63], v[80:81], v[4:5] op_sel_hi:[1,0,1]
	s_waitcnt vmcnt(11)
	v_pk_fma_f32 v[6:7], v[64:65], v[20:21], v[6:7] op_sel_hi:[1,0,1]
	v_pk_fma_f32 v[8:9], v[64:65], v[28:29], v[8:9] op_sel_hi:[1,0,1]
	v_pk_fma_f32 v[10:11], v[64:65], v[36:37], v[10:11] op_sel_hi:[1,0,1]
	v_pk_fma_f32 v[12:13], v[64:65], v[44:45], v[12:13] op_sel_hi:[1,0,1]
	v_pk_fma_f32 v[4:5], v[64:65], v[52:53], v[4:5] op_sel_hi:[1,0,1]
	s_waitcnt vmcnt(10)
	v_pk_fma_f32 v[6:7], v[66:67], v[20:21], v[6:7] op_sel:[0,1,0]
	v_pk_fma_f32 v[8:9], v[66:67], v[28:29], v[8:9] op_sel:[0,1,0]
	v_pk_fma_f32 v[10:11], v[66:67], v[36:37], v[10:11] op_sel:[0,1,0]
	v_pk_fma_f32 v[12:13], v[66:67], v[44:45], v[12:13] op_sel:[0,1,0]
	v_pk_fma_f32 v[4:5], v[66:67], v[52:53], v[4:5] op_sel:[0,1,0]
	s_waitcnt vmcnt(9)
	v_pk_fma_f32 v[6:7], v[68:69], v[22:23], v[6:7] op_sel_hi:[1,0,1]
	v_pk_fma_f32 v[8:9], v[68:69], v[30:31], v[8:9] op_sel_hi:[1,0,1]
	v_pk_fma_f32 v[10:11], v[68:69], v[38:39], v[10:11] op_sel_hi:[1,0,1]
	v_pk_fma_f32 v[12:13], v[68:69], v[46:47], v[12:13] op_sel_hi:[1,0,1]
	v_pk_fma_f32 v[4:5], v[68:69], v[54:55], v[4:5] op_sel_hi:[1,0,1]
	s_waitcnt vmcnt(8)
	v_pk_fma_f32 v[6:7], v[70:71], v[82:83], v[6:7] op_sel_hi:[1,0,1]
	v_pk_fma_f32 v[8:9], v[70:71], v[84:85], v[8:9] op_sel_hi:[1,0,1]
	v_pk_fma_f32 v[10:11], v[70:71], v[86:87], v[10:11] op_sel_hi:[1,0,1]
	v_pk_fma_f32 v[12:13], v[70:71], v[88:89], v[12:13] op_sel_hi:[1,0,1]
	v_pk_fma_f32 v[4:5], v[70:71], v[90:91], v[4:5] op_sel_hi:[1,0,1]
	v_lshl_add_u64 v[108:109], v[0:1], 0, s[6:7]
	s_add_u32 s6, s6, 0x30000
	s_addc_u32 s7, s7, 0
	global_load_dwordx2 v[56:57], v[108:109], off
	v_lshl_add_u64 v[110:111], v[108:109], 0, s[20:21]
	global_load_dwordx2 v[58:59], v[110:111], off
	v_lshl_add_u64 v[112:113], v[110:111], 0, s[20:21]
	global_load_dwordx2 v[60:61], v[112:113], off
	v_lshl_add_u64 v[114:115], v[112:113], 0, s[20:21]
	global_load_dwordx2 v[62:63], v[114:115], off
	v_lshl_add_u64 v[116:117], v[114:115], 0, s[20:21]
	global_load_dwordx2 v[64:65], v[116:117], off
	v_lshl_add_u64 v[118:119], v[116:117], 0, s[20:21]
	global_load_dwordx2 v[66:67], v[118:119], off
	v_lshl_add_u64 v[120:121], v[118:119], 0, s[20:21]
	global_load_dwordx2 v[68:69], v[120:121], off
	v_lshl_add_u64 v[122:123], v[120:121], 0, s[20:21]
	global_load_dwordx2 v[70:71], v[122:123], off
	v_mov_b32_e32 v52, s9
	s_add_i32 s9, s9, 32
	ds_read_b128 v[16:19], v52
	ds_read_b128 v[20:23], v52 offset:16
	ds_read_b128 v[24:27], v52 offset:4096
	ds_read_b128 v[28:31], v52 offset:4112
	ds_read_b128 v[32:35], v52 offset:8192
	ds_read_b128 v[36:39], v52 offset:8208
	ds_read_b128 v[40:43], v52 offset:12288
	ds_read_b128 v[44:47], v52 offset:12304
	ds_read_b128 v[48:51], v52 offset:16384
	ds_read_b128 v[52:55], v52 offset:16400
	s_waitcnt lgkmcnt(0)
	v_mov_b32_e32 v72, v19
	v_mov_b32_e32 v74, v27
	v_mov_b32_e32 v76, v35
	v_mov_b32_e32 v78, v43
	v_mov_b32_e32 v80, v51
	v_mov_b32_e32 v82, v23
	v_mov_b32_e32 v84, v31
	v_mov_b32_e32 v86, v39
	v_mov_b32_e32 v88, v47
	v_mov_b32_e32 v90, v55
	s_waitcnt vmcnt(15)
	v_pk_fma_f32 v[6:7], v[92:93], v[16:17], v[6:7] op_sel_hi:[1,0,1]
	v_pk_fma_f32 v[8:9], v[92:93], v[24:25], v[8:9] op_sel_hi:[1,0,1]
	v_pk_fma_f32 v[10:11], v[92:93], v[32:33], v[10:11] op_sel_hi:[1,0,1]
	v_pk_fma_f32 v[12:13], v[92:93], v[40:41], v[12:13] op_sel_hi:[1,0,1]
	v_pk_fma_f32 v[4:5], v[92:93], v[48:49], v[4:5] op_sel_hi:[1,0,1]
	s_waitcnt vmcnt(14)
	v_pk_fma_f32 v[6:7], v[94:95], v[16:17], v[6:7] op_sel:[0,1,0]
	v_pk_fma_f32 v[8:9], v[94:95], v[24:25], v[8:9] op_sel:[0,1,0]
	v_pk_fma_f32 v[10:11], v[94:95], v[32:33], v[10:11] op_sel:[0,1,0]
	v_pk_fma_f32 v[12:13], v[94:95], v[40:41], v[12:13] op_sel:[0,1,0]
	v_pk_fma_f32 v[4:5], v[94:95], v[48:49], v[4:5] op_sel:[0,1,0]
	s_waitcnt vmcnt(13)
	v_pk_fma_f32 v[6:7], v[96:97], v[18:19], v[6:7] op_sel_hi:[1,0,1]
	v_pk_fma_f32 v[8:9], v[96:97], v[26:27], v[8:9] op_sel_hi:[1,0,1]
	v_pk_fma_f32 v[10:11], v[96:97], v[34:35], v[10:11] op_sel_hi:[1,0,1]
	v_pk_fma_f32 v[12:13], v[96:97], v[42:43], v[12:13] op_sel_hi:[1,0,1]
	v_pk_fma_f32 v[4:5], v[96:97], v[50:51], v[4:5] op_sel_hi:[1,0,1]
	s_waitcnt vmcnt(12)
; __device__ __forceinline__ void prologue_phase(const Args& a, LAS unsigned char* lds) {
;     ...
;         const float* wp = a.ada_w + ((size_t)l * DM + 128 * w) * 6144 + j;
; #pragma unroll 8
;         for (int kk = 0; kk < 128; ++kk) { const int k = 128 * w + kk; const f32x2_t wv = *(const f32x2_t*)(wp + (size_t)kk * 6144);
; #pragma unroll
;             for (int s = 0; s < 5; ++s) { const float sv = sil[s * DM + k]; acc[s][0] += sv * wv.x; acc[s][1] += sv * wv.y; } }
	v_pk_fma_f32 v[6:7], v[98:99], v[72:73], v[6:7] op_sel_hi:[1,0,1]
	v_pk_fma_f32 v[8:9], v[98:99], v[74:75], v[8:9] op_sel_hi:[1,0,1]
	v_pk_fma_f32 v[10:11], v[98:99], v[76:77], v[10:11] op_sel_hi:[1,0,1]
	v_pk_fma_f32 v[12:13], v[98:99], v[78:79], v[12:13] op_sel_hi:[1,0,1]
	v_pk_fma_f32 v[4:5], v[98:99], v[80:81], v[4:5] op_sel_hi:[1,0,1]
	s_waitcnt vmcnt(11)
	v_pk_fma_f32 v[6:7], v[100:101], v[20:21], v[6:7] op_sel_hi:[1,0,1]
	v_pk_fma_f32 v[8:9], v[100:101], v[28:29], v[8:9] op_sel_hi:[1,0,1]
	v_pk_fma_f32 v[10:11], v[100:101], v[36:37], v[10:11] op_sel_hi:[1,0,1]
	v_pk_fma_f32 v[12:13], v[100:101], v[44:45], v[12:13] op_sel_hi:[1,0,1]
	v_pk_fma_f32 v[4:5], v[100:101], v[52:53], v[4:5] op_sel_hi:[1,0,1]
	s_waitcnt vmcnt(10)
	v_pk_fma_f32 v[6:7], v[102:103], v[20:21], v[6:7] op_sel:[0,1,0]
	v_pk_fma_f32 v[8:9], v[102:103], v[28:29], v[8:9] op_sel:[0,1,0]
	v_pk_fma_f32 v[10:11], v[102:103], v[36:37], v[10:11] op_sel:[0,1,0]
	v_pk_fma_f32 v[12:13], v[102:103], v[44:45], v[12:13] op_sel:[0,1,0]
	v_pk_fma_f32 v[4:5], v[102:103], v[52:53], v[4:5] op_sel:[0,1,0]
	s_waitcnt vmcnt(9)
	v_pk_fma_f32 v[6:7], v[104:105], v[22:23], v[6:7] op_sel_hi:[1,0,1]
	v_pk_fma_f32 v[8:9], v[104:105], v[30:31], v[8:9] op_sel_hi:[1,0,1]
	v_pk_fma_f32 v[10:11], v[104:105], v[38:39], v[10:11] op_sel_hi:[1,0,1]
	v_pk_fma_f32 v[12:13], v[104:105], v[46:47], v[12:13] op_sel_hi:[1,0,1]
	v_pk_fma_f32 v[4:5], v[104:105], v[54:55], v[4:5] op_sel_hi:[1,0,1]
	s_waitcnt vmcnt(8)
	v_pk_fma_f32 v[6:7], v[106:107], v[82:83], v[6:7] op_sel_hi:[1,0,1]
	v_pk_fma_f32 v[8:9], v[106:107], v[84:85], v[8:9] op_sel_hi:[1,0,1]
	v_pk_fma_f32 v[10:11], v[106:107], v[86:87], v[10:11] op_sel_hi:[1,0,1]
	v_pk_fma_f32 v[12:13], v[106:107], v[88:89], v[12:13] op_sel_hi:[1,0,1]
	v_pk_fma_f32 v[4:5], v[106:107], v[90:91], v[4:5] op_sel_hi:[1,0,1]
	v_lshl_add_u64 v[108:109], v[0:1], 0, s[6:7]
	s_add_u32 s6, s6, 0x30000
	s_addc_u32 s7, s7, 0
	global_load_dwordx2 v[92:93], v[108:109], off
	v_lshl_add_u64 v[110:111], v[108:109], 0, s[20:21]
	global_load_dwordx2 v[94:95], v[110:111], off
	v_lshl_add_u64 v[112:113], v[110:111], 0, s[20:21]
	global_load_dwordx2 v[96:97], v[112:113], off
	v_lshl_add_u64 v[114:115], v[112:113], 0, s[20:21]
	global_load_dwordx2 v[98:99], v[114:115], off
	v_lshl_add_u64 v[116:117], v[114:115], 0, s[20:21]
	global_load_dwordx2 v[100:101], v[116:117], off
	v_lshl_add_u64 v[118:119], v[116:117], 0, s[20:21]
	global_load_dwordx2 v[102:103], v[118:119], off
	v_lshl_add_u64 v[120:121], v[118:119], 0, s[20:21]
	global_load_dwordx2 v[104:105], v[120:121], off
	v_lshl_add_u64 v[122:123], v[120:121], 0, s[20:21]
	global_load_dwordx2 v[106:107], v[122:123], off
	v_mov_b32_e32 v52, s9
	s_add_i32 s9, s9, 32
	ds_read_b128 v[16:19], v52
	ds_read_b128 v[20:23], v52 offset:16
	ds_read_b128 v[24:27], v52 offset:4096
	ds_read_b128 v[28:31], v52 offset:4112
	ds_read_b128 v[32:35], v52 offset:8192
	ds_read_b128 v[36:39], v52 offset:8208
	ds_read_b128 v[40:43], v52 offset:12288
	ds_read_b128 v[44:47], v52 offset:12304
	ds_read_b128 v[48:51], v52 offset:16384
	ds_read_b128 v[52:55], v52 offset:16400
	s_waitcnt lgkmcnt(0)
	v_mov_b32_e32 v72, v19
	v_mov_b32_e32 v74, v27
	v_mov_b32_e32 v76, v35
	v_mov_b32_e32 v78, v43
	v_mov_b32_e32 v80, v51
	v_mov_b32_e32 v82, v23
	v_mov_b32_e32 v84, v31
	v_mov_b32_e32 v86, v39
	v_mov_b32_e32 v88, v47
	v_mov_b32_e32 v90, v55
	s_waitcnt vmcnt(15)
	v_pk_fma_f32 v[6:7], v[56:57], v[16:17], v[6:7] op_sel_hi:[1,0,1]
	v_pk_fma_f32 v[8:9], v[56:57], v[24:25], v[8:9] op_sel_hi:[1,0,1]
	v_pk_fma_f32 v[10:11], v[56:57], v[32:33], v[10:11] op_sel_hi:[1,0,1]
	v_pk_fma_f32 v[12:13], v[56:57], v[40:41], v[12:13] op_sel_hi:[1,0,1]
	v_pk_fma_f32 v[4:5], v[56:57], v[48:49], v[4:5] op_sel_hi:[1,0,1]
	s_waitcnt vmcnt(14)
	v_pk_fma_f32 v[6:7], v[58:59], v[16:17], v[6:7] op_sel:[0,1,0]
	v_pk_fma_f32 v[8:9], v[58:59], v[24:25], v[8:9] op_sel:[0,1,0]
	v_pk_fma_f32 v[10:11], v[58:59], v[32:33], v[10:11] op_sel:[0,1,0]
	v_pk_fma_f32 v[12:13], v[58:59], v[40:41], v[12:13] op_sel:[0,1,0]
	v_pk_fma_f32 v[4:5], v[58:59], v[48:49], v[4:5] op_sel:[0,1,0]
	s_waitcnt vmcnt(13)
	v_pk_fma_f32 v[6:7], v[60:61], v[18:19], v[6:7] op_sel_hi:[1,0,1]
	v_pk_fma_f32 v[8:9], v[60:61], v[26:27], v[8:9] op_sel_hi:[1,0,1]
	v_pk_fma_f32 v[10:11], v[60:61], v[34:35], v[10:11] op_sel_hi:[1,0,1]
	v_pk_fma_f32 v[12:13], v[60:61], v[42:43], v[12:13] op_sel_hi:[1,0,1]
	v_pk_fma_f32 v[4:5], v[60:61], v[50:51], v[4:5] op_sel_hi:[1,0,1]
	s_waitcnt vmcnt(12)
	v_pk_fma_f32 v[6:7], v[62:63], v[72:73], v[6:7] op_sel_hi:[1,0,1]
	v_pk_fma_f32 v[8:9], v[62:63], v[74:75], v[8:9] op_sel_hi:[1,0,1]
	v_pk_fma_f32 v[10:11], v[62:63], v[76:77], v[10:11] op_sel_hi:[1,0,1]
	v_pk_fma_f32 v[12:13], v[62:63], v[78:79], v[12:13] op_sel_hi:[1,0,1]
	v_pk_fma_f32 v[4:5], v[62:63], v[80:81], v[4:5] op_sel_hi:[1,0,1]
	s_waitcnt vmcnt(11)
	v_pk_fma_f32 v[6:7], v[64:65], v[20:21], v[6:7] op_sel_hi:[1,0,1]
	v_pk_fma_f32 v[8:9], v[64:65], v[28:29], v[8:9] op_sel_hi:[1,0,1]
	v_pk_fma_f32 v[10:11], v[64:65], v[36:37], v[10:11] op_sel_hi:[1,0,1]
	v_pk_fma_f32 v[12:13], v[64:65], v[44:45], v[12:13] op_sel_hi:[1,0,1]
	v_pk_fma_f32 v[4:5], v[64:65], v[52:53], v[4:5] op_sel_hi:[1,0,1]
	s_waitcnt vmcnt(10)
	v_pk_fma_f32 v[6:7], v[66:67], v[20:21], v[6:7] op_sel:[0,1,0]
	v_pk_fma_f32 v[8:9], v[66:67], v[28:29], v[8:9] op_sel:[0,1,0]
	v_pk_fma_f32 v[10:11], v[66:67], v[36:37], v[10:11] op_sel:[0,1,0]
	v_pk_fma_f32 v[12:13], v[66:67], v[44:45], v[12:13] op_sel:[0,1,0]
	v_pk_fma_f32 v[4:5], v[66:67], v[52:53], v[4:5] op_sel:[0,1,0]
	s_waitcnt vmcnt(9)
; __device__ __forceinline__ void prologue_phase(const Args& a, LAS unsigned char* lds) {
;     ...
;         const float* wp = a.ada_w + ((size_t)l * DM + 128 * w) * 6144 + j;
; #pragma unroll 8
;         for (int kk = 0; kk < 128; ++kk) { const int k = 128 * w + kk; const f32x2_t wv = *(const f32x2_t*)(wp + (size_t)kk * 6144);
; #pragma unroll
;             for (int s = 0; s < 5; ++s) { const float sv = sil[s * DM + k]; acc[s][0] += sv * wv.x; acc[s][1] += sv * wv.y; } }
	v_pk_fma_f32 v[6:7], v[68:69], v[22:23], v[6:7] op_sel_hi:[1,0,1]
	v_pk_fma_f32 v[8:9], v[68:69], v[30:31], v[8:9] op_sel_hi:[1,0,1]
	v_pk_fma_f32 v[10:11], v[68:69], v[38:39], v[10:11] op_sel_hi:[1,0,1]
	v_pk_fma_f32 v[12:13], v[68:69], v[46:47], v[12:13] op_sel_hi:[1,0,1]
	v_pk_fma_f32 v[4:5], v[68:69], v[54:55], v[4:5] op_sel_hi:[1,0,1]
	s_waitcnt vmcnt(8)
	v_pk_fma_f32 v[6:7], v[70:71], v[82:83], v[6:7] op_sel_hi:[1,0,1]
	v_pk_fma_f32 v[8:9], v[70:71], v[84:85], v[8:9] op_sel_hi:[1,0,1]
	v_pk_fma_f32 v[10:11], v[70:71], v[86:87], v[10:11] op_sel_hi:[1,0,1]
	v_pk_fma_f32 v[12:13], v[70:71], v[88:89], v[12:13] op_sel_hi:[1,0,1]
	v_pk_fma_f32 v[4:5], v[70:71], v[90:91], v[4:5] op_sel_hi:[1,0,1]
	v_lshl_add_u64 v[108:109], v[0:1], 0, s[6:7]
	s_add_u32 s6, s6, 0x30000
	s_addc_u32 s7, s7, 0
	global_load_dwordx2 v[56:57], v[108:109], off
	v_lshl_add_u64 v[110:111], v[108:109], 0, s[20:21]
	global_load_dwordx2 v[58:59], v[110:111], off
	v_lshl_add_u64 v[112:113], v[110:111], 0, s[20:21]
	global_load_dwordx2 v[60:61], v[112:113], off
	v_lshl_add_u64 v[114:115], v[112:113], 0, s[20:21]
	global_load_dwordx2 v[62:63], v[114:115], off
	v_lshl_add_u64 v[116:117], v[114:115], 0, s[20:21]
	global_load_dwordx2 v[64:65], v[116:117], off
	v_lshl_add_u64 v[118:119], v[116:117], 0, s[20:21]
	global_load_dwordx2 v[66:67], v[118:119], off
	v_lshl_add_u64 v[120:121], v[118:119], 0, s[20:21]
	global_load_dwordx2 v[68:69], v[120:121], off
	v_lshl_add_u64 v[122:123], v[120:121], 0, s[20:21]
	global_load_dwordx2 v[70:71], v[122:123], off
	v_mov_b32_e32 v52, s9
	s_add_i32 s9, s9, 32
	ds_read_b128 v[16:19], v52
	ds_read_b128 v[20:23], v52 offset:16
	ds_read_b128 v[24:27], v52 offset:4096
	ds_read_b128 v[28:31], v52 offset:4112
	ds_read_b128 v[32:35], v52 offset:8192
	ds_read_b128 v[36:39], v52 offset:8208
	ds_read_b128 v[40:43], v52 offset:12288
	ds_read_b128 v[44:47], v52 offset:12304
	ds_read_b128 v[48:51], v52 offset:16384
	ds_read_b128 v[52:55], v52 offset:16400
	s_waitcnt lgkmcnt(0)
	v_mov_b32_e32 v72, v19
	v_mov_b32_e32 v74, v27
	v_mov_b32_e32 v76, v35
	v_mov_b32_e32 v78, v43
	v_mov_b32_e32 v80, v51
	v_mov_b32_e32 v82, v23
	v_mov_b32_e32 v84, v31
	v_mov_b32_e32 v86, v39
	v_mov_b32_e32 v88, v47
	v_mov_b32_e32 v90, v55
	s_waitcnt vmcnt(15)
	v_pk_fma_f32 v[6:7], v[92:93], v[16:17], v[6:7] op_sel_hi:[1,0,1]
	v_pk_fma_f32 v[8:9], v[92:93], v[24:25], v[8:9] op_sel_hi:[1,0,1]
	v_pk_fma_f32 v[10:11], v[92:93], v[32:33], v[10:11] op_sel_hi:[1,0,1]
	v_pk_fma_f32 v[12:13], v[92:93], v[40:41], v[12:13] op_sel_hi:[1,0,1]
	v_pk_fma_f32 v[4:5], v[92:93], v[48:49], v[4:5] op_sel_hi:[1,0,1]
	s_waitcnt vmcnt(14)
	v_pk_fma_f32 v[6:7], v[94:95], v[16:17], v[6:7] op_sel:[0,1,0]
	v_pk_fma_f32 v[8:9], v[94:95], v[24:25], v[8:9] op_sel:[0,1,0]
	v_pk_fma_f32 v[10:11], v[94:95], v[32:33], v[10:11] op_sel:[0,1,0]
	v_pk_fma_f32 v[12:13], v[94:95], v[40:41], v[12:13] op_sel:[0,1,0]
	v_pk_fma_f32 v[4:5], v[94:95], v[48:49], v[4:5] op_sel:[0,1,0]
	s_waitcnt vmcnt(13)
	v_pk_fma_f32 v[6:7], v[96:97], v[18:19], v[6:7] op_sel_hi:[1,0,1]
	v_pk_fma_f32 v[8:9], v[96:97], v[26:27], v[8:9] op_sel_hi:[1,0,1]
	v_pk_fma_f32 v[10:11], v[96:97], v[34:35], v[10:11] op_sel_hi:[1,0,1]
	v_pk_fma_f32 v[12:13], v[96:97], v[42:43], v[12:13] op_sel_hi:[1,0,1]
	v_pk_fma_f32 v[4:5], v[96:97], v[50:51], v[4:5] op_sel_hi:[1,0,1]
	s_waitcnt vmcnt(12)
	v_pk_fma_f32 v[6:7], v[98:99], v[72:73], v[6:7] op_sel_hi:[1,0,1]
	v_pk_fma_f32 v[8:9], v[98:99], v[74:75], v[8:9] op_sel_hi:[1,0,1]
	v_pk_fma_f32 v[10:11], v[98:99], v[76:77], v[10:11] op_sel_hi:[1,0,1]
	v_pk_fma_f32 v[12:13], v[98:99], v[78:79], v[12:13] op_sel_hi:[1,0,1]
	v_pk_fma_f32 v[4:5], v[98:99], v[80:81], v[4:5] op_sel_hi:[1,0,1]
	s_waitcnt vmcnt(11)
	v_pk_fma_f32 v[6:7], v[100:101], v[20:21], v[6:7] op_sel_hi:[1,0,1]
	v_pk_fma_f32 v[8:9], v[100:101], v[28:29], v[8:9] op_sel_hi:[1,0,1]
	v_pk_fma_f32 v[10:11], v[100:101], v[36:37], v[10:11] op_sel_hi:[1,0,1]
	v_pk_fma_f32 v[12:13], v[100:101], v[44:45], v[12:13] op_sel_hi:[1,0,1]
	v_pk_fma_f32 v[4:5], v[100:101], v[52:53], v[4:5] op_sel_hi:[1,0,1]
	s_waitcnt vmcnt(10)
	v_pk_fma_f32 v[6:7], v[102:103], v[20:21], v[6:7] op_sel:[0,1,0]
	v_pk_fma_f32 v[8:9], v[102:103], v[28:29], v[8:9] op_sel:[0,1,0]
	v_pk_fma_f32 v[10:11], v[102:103], v[36:37], v[10:11] op_sel:[0,1,0]
	v_pk_fma_f32 v[12:13], v[102:103], v[44:45], v[12:13] op_sel:[0,1,0]
	v_pk_fma_f32 v[4:5], v[102:103], v[52:53], v[4:5] op_sel:[0,1,0]
	s_waitcnt vmcnt(9)
	v_pk_fma_f32 v[6:7], v[104:105], v[22:23], v[6:7] op_sel_hi:[1,0,1]
	v_pk_fma_f32 v[8:9], v[104:105], v[30:31], v[8:9] op_sel_hi:[1,0,1]
	v_pk_fma_f32 v[10:11], v[104:105], v[38:39], v[10:11] op_sel_hi:[1,0,1]
	v_pk_fma_f32 v[12:13], v[104:105], v[46:47], v[12:13] op_sel_hi:[1,0,1]
	v_pk_fma_f32 v[4:5], v[104:105], v[54:55], v[4:5] op_sel_hi:[1,0,1]
	s_waitcnt vmcnt(8)
	v_pk_fma_f32 v[6:7], v[106:107], v[82:83], v[6:7] op_sel_hi:[1,0,1]
	v_pk_fma_f32 v[8:9], v[106:107], v[84:85], v[8:9] op_sel_hi:[1,0,1]
	v_pk_fma_f32 v[10:11], v[106:107], v[86:87], v[10:11] op_sel_hi:[1,0,1]
	v_pk_fma_f32 v[12:13], v[106:107], v[88:89], v[12:13] op_sel_hi:[1,0,1]
	v_pk_fma_f32 v[4:5], v[106:107], v[90:91], v[4:5] op_sel_hi:[1,0,1]
	v_lshl_add_u64 v[108:109], v[0:1], 0, s[6:7]
	s_add_u32 s6, s6, 0x30000
	s_addc_u32 s7, s7, 0
	global_load_dwordx2 v[92:93], v[108:109], off
	v_lshl_add_u64 v[110:111], v[108:109], 0, s[20:21]
	global_load_dwordx2 v[94:95], v[110:111], off
	v_lshl_add_u64 v[112:113], v[110:111], 0, s[20:21]
	global_load_dwordx2 v[96:97], v[112:113], off
	v_lshl_add_u64 v[114:115], v[112:113], 0, s[20:21]
	global_load_dwordx2 v[98:99], v[114:115], off
	v_lshl_add_u64 v[116:117], v[114:115], 0, s[20:21]
	global_load_dwordx2 v[100:101], v[116:117], off
	v_lshl_add_u64 v[118:119], v[116:117], 0, s[20:21]
	global_load_dwordx2 v[102:103], v[118:119], off
	v_lshl_add_u64 v[120:121], v[118:119], 0, s[20:21]
	global_load_dwordx2 v[104:105], v[120:121], off
	v_lshl_add_u64 v[122:123], v[120:121], 0, s[20:21]
	global_load_dwordx2 v[106:107], v[122:123], off
	v_mov_b32_e32 v52, s9
	s_add_i32 s9, s9, 32
	ds_read_b128 v[16:19], v52
	ds_read_b128 v[20:23], v52 offset:16
	ds_read_b128 v[24:27], v52 offset:4096
	ds_read_b128 v[28:31], v52 offset:4112
	ds_read_b128 v[32:35], v52 offset:8192
	ds_read_b128 v[36:39], v52 offset:8208
	ds_read_b128 v[40:43], v52 offset:12288
	ds_read_b128 v[44:47], v52 offset:12304
	ds_read_b128 v[48:51], v52 offset:16384
	ds_read_b128 v[52:55], v52 offset:16400
	s_waitcnt lgkmcnt(0)
; #define LAS __attribute__((address_space(3)))
; __device__ __forceinline__ void prologue_phase(const Args& a, LAS unsigned char* lds) {
;     ...
;         const float* wp = a.ada_w + ((size_t)l * DM + 128 * w) * 6144 + j;
; #pragma unroll 8
;         for (int kk = 0; kk < 128; ++kk) { const int k = 128 * w + kk; const f32x2_t wv = *(const f32x2_t*)(wp + (size_t)kk * 6144);
; #pragma unroll
;             for (int s = 0; s < 5; ++s) { const float sv = sil[s * DM + k]; acc[s][0] += sv * wv.x; acc[s][1] += sv * wv.y; } }
;         LAS float* part = (LAS float*)lds;
; #pragma unroll
;         for (int s = 0; s < 5; ++s) { part[(w * 5 + s) * 128 + 2 * lane] = acc[s][0]; part[(w * 5 + s) * 128 + 2 * lane + 1] = acc[s][1]; }
	v_mov_b32_e32 v72, v19
	v_mov_b32_e32 v74, v27
	v_mov_b32_e32 v76, v35
	v_mov_b32_e32 v78, v43
	v_mov_b32_e32 v80, v51
	v_mov_b32_e32 v82, v23
	v_mov_b32_e32 v84, v31
	v_mov_b32_e32 v86, v39
	v_mov_b32_e32 v88, v47
	v_mov_b32_e32 v90, v55
	s_waitcnt vmcnt(15)
	v_pk_fma_f32 v[6:7], v[56:57], v[16:17], v[6:7] op_sel_hi:[1,0,1]
	v_pk_fma_f32 v[8:9], v[56:57], v[24:25], v[8:9] op_sel_hi:[1,0,1]
	v_pk_fma_f32 v[10:11], v[56:57], v[32:33], v[10:11] op_sel_hi:[1,0,1]
	v_pk_fma_f32 v[12:13], v[56:57], v[40:41], v[12:13] op_sel_hi:[1,0,1]
	v_pk_fma_f32 v[4:5], v[56:57], v[48:49], v[4:5] op_sel_hi:[1,0,1]
	s_waitcnt vmcnt(14)
	v_pk_fma_f32 v[6:7], v[58:59], v[16:17], v[6:7] op_sel:[0,1,0]
	v_pk_fma_f32 v[8:9], v[58:59], v[24:25], v[8:9] op_sel:[0,1,0]
	v_pk_fma_f32 v[10:11], v[58:59], v[32:33], v[10:11] op_sel:[0,1,0]
	v_pk_fma_f32 v[12:13], v[58:59], v[40:41], v[12:13] op_sel:[0,1,0]
	v_pk_fma_f32 v[4:5], v[58:59], v[48:49], v[4:5] op_sel:[0,1,0]
	s_waitcnt vmcnt(13)
	v_pk_fma_f32 v[6:7], v[60:61], v[18:19], v[6:7] op_sel_hi:[1,0,1]
	v_pk_fma_f32 v[8:9], v[60:61], v[26:27], v[8:9] op_sel_hi:[1,0,1]
	v_pk_fma_f32 v[10:11], v[60:61], v[34:35], v[10:11] op_sel_hi:[1,0,1]
	v_pk_fma_f32 v[12:13], v[60:61], v[42:43], v[12:13] op_sel_hi:[1,0,1]
	v_pk_fma_f32 v[4:5], v[60:61], v[50:51], v[4:5] op_sel_hi:[1,0,1]
	s_waitcnt vmcnt(12)
	v_pk_fma_f32 v[6:7], v[62:63], v[72:73], v[6:7] op_sel_hi:[1,0,1]
	v_pk_fma_f32 v[8:9], v[62:63], v[74:75], v[8:9] op_sel_hi:[1,0,1]
	v_pk_fma_f32 v[10:11], v[62:63], v[76:77], v[10:11] op_sel_hi:[1,0,1]
	v_pk_fma_f32 v[12:13], v[62:63], v[78:79], v[12:13] op_sel_hi:[1,0,1]
	v_pk_fma_f32 v[4:5], v[62:63], v[80:81], v[4:5] op_sel_hi:[1,0,1]
	s_waitcnt vmcnt(11)
	v_pk_fma_f32 v[6:7], v[64:65], v[20:21], v[6:7] op_sel_hi:[1,0,1]
	v_pk_fma_f32 v[8:9], v[64:65], v[28:29], v[8:9] op_sel_hi:[1,0,1]
	v_pk_fma_f32 v[10:11], v[64:65], v[36:37], v[10:11] op_sel_hi:[1,0,1]
	v_pk_fma_f32 v[12:13], v[64:65], v[44:45], v[12:13] op_sel_hi:[1,0,1]
	v_pk_fma_f32 v[4:5], v[64:65], v[52:53], v[4:5] op_sel_hi:[1,0,1]
	s_waitcnt vmcnt(10)
	v_pk_fma_f32 v[6:7], v[66:67], v[20:21], v[6:7] op_sel:[0,1,0]
	v_pk_fma_f32 v[8:9], v[66:67], v[28:29], v[8:9] op_sel:[0,1,0]
	v_pk_fma_f32 v[10:11], v[66:67], v[36:37], v[10:11] op_sel:[0,1,0]
	v_pk_fma_f32 v[12:13], v[66:67], v[44:45], v[12:13] op_sel:[0,1,0]
	v_pk_fma_f32 v[4:5], v[66:67], v[52:53], v[4:5] op_sel:[0,1,0]
	s_waitcnt vmcnt(9)
	v_pk_fma_f32 v[6:7], v[68:69], v[22:23], v[6:7] op_sel_hi:[1,0,1]
	v_pk_fma_f32 v[8:9], v[68:69], v[30:31], v[8:9] op_sel_hi:[1,0,1]
	v_pk_fma_f32 v[10:11], v[68:69], v[38:39], v[10:11] op_sel_hi:[1,0,1]
	v_pk_fma_f32 v[12:13], v[68:69], v[46:47], v[12:13] op_sel_hi:[1,0,1]
	v_pk_fma_f32 v[4:5], v[68:69], v[54:55], v[4:5] op_sel_hi:[1,0,1]
	s_waitcnt vmcnt(8)
	v_pk_fma_f32 v[6:7], v[70:71], v[82:83], v[6:7] op_sel_hi:[1,0,1]
	v_pk_fma_f32 v[8:9], v[70:71], v[84:85], v[8:9] op_sel_hi:[1,0,1]
	v_pk_fma_f32 v[10:11], v[70:71], v[86:87], v[10:11] op_sel_hi:[1,0,1]
	v_pk_fma_f32 v[12:13], v[70:71], v[88:89], v[12:13] op_sel_hi:[1,0,1]
	v_pk_fma_f32 v[4:5], v[70:71], v[90:91], v[4:5] op_sel_hi:[1,0,1]
	v_mov_b32_e32 v52, s9
	s_add_i32 s9, s9, 32
	ds_read_b128 v[16:19], v52
	ds_read_b128 v[20:23], v52 offset:16
	ds_read_b128 v[24:27], v52 offset:4096
	ds_read_b128 v[28:31], v52 offset:4112
	ds_read_b128 v[32:35], v52 offset:8192
	ds_read_b128 v[36:39], v52 offset:8208
	ds_read_b128 v[40:43], v52 offset:12288
	ds_read_b128 v[44:47], v52 offset:12304
	ds_read_b128 v[48:51], v52 offset:16384
	ds_read_b128 v[52:55], v52 offset:16400
	s_waitcnt lgkmcnt(0)
	v_mov_b32_e32 v72, v19
	v_mov_b32_e32 v74, v27
	v_mov_b32_e32 v76, v35
	v_mov_b32_e32 v78, v43
	v_mov_b32_e32 v80, v51
	v_mov_b32_e32 v82, v23
	v_mov_b32_e32 v84, v31
	v_mov_b32_e32 v86, v39
	v_mov_b32_e32 v88, v47
	v_mov_b32_e32 v90, v55
	s_waitcnt vmcnt(7)
	v_pk_fma_f32 v[6:7], v[92:93], v[16:17], v[6:7] op_sel_hi:[1,0,1]
	v_pk_fma_f32 v[8:9], v[92:93], v[24:25], v[8:9] op_sel_hi:[1,0,1]
	v_pk_fma_f32 v[10:11], v[92:93], v[32:33], v[10:11] op_sel_hi:[1,0,1]
	v_pk_fma_f32 v[12:13], v[92:93], v[40:41], v[12:13] op_sel_hi:[1,0,1]
	v_pk_fma_f32 v[4:5], v[92:93], v[48:49], v[4:5] op_sel_hi:[1,0,1]
	s_waitcnt vmcnt(6)
	v_pk_fma_f32 v[6:7], v[94:95], v[16:17], v[6:7] op_sel:[0,1,0]
	v_pk_fma_f32 v[8:9], v[94:95], v[24:25], v[8:9] op_sel:[0,1,0]
	v_pk_fma_f32 v[10:11], v[94:95], v[32:33], v[10:11] op_sel:[0,1,0]
	v_pk_fma_f32 v[12:13], v[94:95], v[40:41], v[12:13] op_sel:[0,1,0]
	v_pk_fma_f32 v[4:5], v[94:95], v[48:49], v[4:5] op_sel:[0,1,0]
	s_waitcnt vmcnt(5)
	v_pk_fma_f32 v[6:7], v[96:97], v[18:19], v[6:7] op_sel_hi:[1,0,1]
	v_pk_fma_f32 v[8:9], v[96:97], v[26:27], v[8:9] op_sel_hi:[1,0,1]
	v_pk_fma_f32 v[10:11], v[96:97], v[34:35], v[10:11] op_sel_hi:[1,0,1]
	v_pk_fma_f32 v[12:13], v[96:97], v[42:43], v[12:13] op_sel_hi:[1,0,1]
	v_pk_fma_f32 v[4:5], v[96:97], v[50:51], v[4:5] op_sel_hi:[1,0,1]
	s_waitcnt vmcnt(4)
	v_pk_fma_f32 v[6:7], v[98:99], v[72:73], v[6:7] op_sel_hi:[1,0,1]
	v_pk_fma_f32 v[8:9], v[98:99], v[74:75], v[8:9] op_sel_hi:[1,0,1]
	v_pk_fma_f32 v[10:11], v[98:99], v[76:77], v[10:11] op_sel_hi:[1,0,1]
	v_pk_fma_f32 v[12:13], v[98:99], v[78:79], v[12:13] op_sel_hi:[1,0,1]
	v_pk_fma_f32 v[4:5], v[98:99], v[80:81], v[4:5] op_sel_hi:[1,0,1]
	s_waitcnt vmcnt(3)
	v_pk_fma_f32 v[6:7], v[100:101], v[20:21], v[6:7] op_sel_hi:[1,0,1]
	v_pk_fma_f32 v[8:9], v[100:101], v[28:29], v[8:9] op_sel_hi:[1,0,1]
	v_pk_fma_f32 v[10:11], v[100:101], v[36:37], v[10:11] op_sel_hi:[1,0,1]
	v_pk_fma_f32 v[12:13], v[100:101], v[44:45], v[12:13] op_sel_hi:[1,0,1]
	v_pk_fma_f32 v[4:5], v[100:101], v[52:53], v[4:5] op_sel_hi:[1,0,1]
	s_waitcnt vmcnt(2)
	v_pk_fma_f32 v[6:7], v[102:103], v[20:21], v[6:7] op_sel:[0,1,0]
	v_pk_fma_f32 v[8:9], v[102:103], v[28:29], v[8:9] op_sel:[0,1,0]
	v_pk_fma_f32 v[10:11], v[102:103], v[36:37], v[10:11] op_sel:[0,1,0]
	v_pk_fma_f32 v[12:13], v[102:103], v[44:45], v[12:13] op_sel:[0,1,0]
	v_pk_fma_f32 v[4:5], v[102:103], v[52:53], v[4:5] op_sel:[0,1,0]
	s_waitcnt vmcnt(1)
	v_pk_fma_f32 v[6:7], v[104:105], v[22:23], v[6:7] op_sel_hi:[1,0,1]
	v_pk_fma_f32 v[8:9], v[104:105], v[30:31], v[8:9] op_sel_hi:[1,0,1]
	v_pk_fma_f32 v[10:11], v[104:105], v[38:39], v[10:11] op_sel_hi:[1,0,1]
	v_pk_fma_f32 v[12:13], v[104:105], v[46:47], v[12:13] op_sel_hi:[1,0,1]
	v_pk_fma_f32 v[4:5], v[104:105], v[54:55], v[4:5] op_sel_hi:[1,0,1]
	s_waitcnt vmcnt(0)
	v_pk_fma_f32 v[6:7], v[106:107], v[82:83], v[6:7] op_sel_hi:[1,0,1]
	v_pk_fma_f32 v[8:9], v[106:107], v[84:85], v[8:9] op_sel_hi:[1,0,1]
	v_pk_fma_f32 v[10:11], v[106:107], v[86:87], v[10:11] op_sel_hi:[1,0,1]
	v_pk_fma_f32 v[12:13], v[106:107], v[88:89], v[12:13] op_sel_hi:[1,0,1]
	v_pk_fma_f32 v[4:5], v[106:107], v[90:91], v[4:5] op_sel_hi:[1,0,1]
	s_mul_i32 s6, s14, 0xa00
	s_add_i32 s6, s6, 0
	v_lshl_add_u32 v0, v15, 2, s6
	s_movk_i32 s6, 0x280
	v_cmp_gt_u32_e32 vcc, s6, v152
	ds_write2st64_b64 v0, v[6:7], v[8:9] offset1:1
	ds_write2st64_b64 v0, v[10:11], v[12:13] offset0:2 offset1:3
	ds_write_b64 v0, v[4:5] offset:2048
	s_waitcnt lgkmcnt(0)
	s_barrier
; __device__ __forceinline__ void prologue_phase(const Args& a, LAS unsigned char* lds) {
;     ...
;         for (int idx = tid; idx < 640; idx += 512) { const int s = idx >> 7, col = idx & 127; float t = 0.f;
; #pragma unroll
;             for (int ww = 0; ww < 8; ++ww) t += part[(ww * 5 + s) * 128 + col];
;             mods[(l * 5 + s) * 6144 + 128 * cgp + col] = t + a.ada_b[l * 6144 + 128 * cgp + col]; }
	s_and_saveexec_b64 s[6:7], vcc
	s_cbranch_execz .LBB0_44
	s_mov_b64 s[8:9], 0x100000
	v_lshl_add_u64 v[0:1], v[2:3], 0, s[8:9]
	s_load_dwordx2 s[10:11], s[0:1], 0x28
	s_and_b64 s[8:9], s[4:5], exec
	s_cselect_b32 s8, 0x1800, 0
	s_add_i32 s9, s3, s8
	s_and_b64 s[4:5], s[4:5], exec
	v_and_b32_e32 v7, 0x7f, v152
	s_cselect_b32 s4, 5, 0
	v_or_b32_e32 v2, s9, v7
	v_mov_b32_e32 v3, 0
	v_lshrrev_b32_e32 v8, 7, v152
	s_waitcnt lgkmcnt(0)
	v_lshl_add_u64 v[4:5], v[2:3], 2, s[10:11]
	v_add_u32_e32 v2, s4, v8
	v_mul_u32_u24_e32 v2, 0x1800, v2
	v_add3_u32 v2, s3, v2, v7
	v_lshlrev_b32_e32 v7, 2, v7
	v_lshl_or_b32 v7, v8, 9, v7
	s_movk_i32 s8, 0x7f
	v_add_u32_e32 v6, 0xfffffe00, v152
	v_add_u32_e32 v7, 0, v7
	s_mov_b64 s[4:5], 0
